# v54 plus P6 and P7: each wave owns 64 contiguous output columns (B rows re-staged) and DPP row_ror:8 merges packed halves so every epilogue store writes whole 128-B lines
# speedup vs baseline: 1.0014x; 1.0010x over previous
.LBB0_503:
	v_readlane_b32 s4, v254, 1
	s_cmp_lt_i32 s4, 7
	s_cselect_b64 s[2:3], -1, 0
	s_and_b64 s[2:3], s[2:3], s[0:1]
	s_andn2_b64 vcc, exec, s[2:3]
	v_readlane_b32 s5, v254, 2
	v_readlane_b32 s6, v254, 3
	v_readlane_b32 s7, v254, 4
	s_cbranch_vccnz .LBB0_528
	s_bfe_u32 s101, s97, 0x10008
	s_lshl_b32 s101, s101, 17
	v_mbcnt_lo_u32_b32 v9, -1, 0
	v_mbcnt_hi_u32_b32 v9, -1, v9
	s_cmpk_gt_i32 s96, 0x7ff
	v_add_u32_e32 v224, s97, v9
	s_nop 0
	v_readfirstlane_b32 s8, v224
	s_cbranch_scc1 .LBB0_528
	s_ashr_i32 s14, s96, 31
	s_lshr_b32 s0, s14, 29
	s_add_i32 s5, s96, s0
	s_and_b32 s0, s5, -8
	s_sub_i32 s6, s96, s0
	s_cmp_gt_i32 s6, -1
	s_cbranch_scc0 .LBB0_507
	s_lshl_b32 s4, s6, 8
	s_cbranch_execz .LBB0_508
	s_branch .LBB0_509

.LBB0_509:
	v_ashrrev_i32_e32 v1, 31, v224
	v_lshrrev_b32_e32 v1, 26, v1
	v_add_u32_e32 v1, v224, v1
	v_ashrrev_i32_e32 v8, 6, v1
	v_bfe_i32 v1, v224, 27, 1
	v_lshlrev_b32_e32 v0, 4, v224
	v_lshrrev_b32_e32 v1, 22, v1
	v_add_u32_e32 v1, v0, v1
	v_and_b32_e32 v1, 0xfffffc00, v1
	v_sub_u32_e32 v1, v0, v1
	v_lshrrev_b32_e32 v2, 4, v1
	v_bitop3_b32 v1, v2, v1, 32 bitop3:0x6c
	v_ashrrev_i32_e32 v3, 31, v1
	v_lshrrev_b32_e32 v3, 26, v3
	v_add_u32_e32 v3, v1, v3
	v_lshlrev_b32_e32 v2, 3, v8
	v_ashrrev_i32_e32 v10, 6, v3
	v_and_b32_e32 v3, 0xc0, v3
	v_and_b32_e32 v2, -16, v2
	v_sub_u32_e32 v1, v1, v3
	v_mov_b32_e32 v3, 1
	v_add_u32_e32 v2, v10, v2
	v_ashrrev_i16_sdwa v1, v3, sext(v1) dst_sel:DWORD dst_unused:UNUSED_PAD src0_sel:DWORD src1_sel:BYTE_0
	s_ashr_i32 s0, s5, 3
	v_lshlrev_b32_e32 v4, 5, v8
	v_bfe_i32 v11, v1, 0, 16
	v_lshlrev_b32_e32 v1, 1, v2
	v_lshrrev_b32_e32 v5, 2, v2
	v_and_b32_e32 v6, 3, v10
	s_mov_b32 s5, 0xfffe0
	v_and_b32_e32 v4, 32, v4
	v_and_b32_e32 v1, 24, v1
	v_and_b32_e32 v5, 4, v5
	v_and_or_b32 v6, v2, s5, v6
	v_or3_b32 v1, v6, v5, v1
	v_add_lshl_u32 v4, v4, v11, 1
	v_add_u32_e32 v0, 0x2000, v0
	v_lshl_add_u32 v130, v1, 12, v4
	v_add_u32_e32 v130, s101, v130
	v_ashrrev_i32_e32 v1, 31, v0
	v_lshrrev_b32_e32 v1, 22, v1
	v_add_u32_e32 v1, v0, v1
	v_ashrrev_i32_e32 v12, 10, v1
	v_mul_i32_i24_e32 v1, 0x400, v12
	v_sub_u32_e32 v0, v0, v1
	v_lshrrev_b32_e32 v1, 4, v0
	v_bitop3_b32 v0, v1, v0, 32 bitop3:0x6c
	v_lshl_add_u32 v128, v2, 12, v4
	v_ashrrev_i32_e32 v2, 31, v0
	s_add_u32 s33, s94, 0x10100000
	v_lshrrev_b32_e32 v2, 26, v2
	s_addc_u32 s52, s95, 0
	v_add_u32_e32 v2, v0, v2
	s_add_i32 s0, s4, s0
	v_lshlrev_b32_e32 v1, 3, v12
	v_ashrrev_i32_e32 v13, 6, v2
	v_and_b32_e32 v2, 0xc0, v2
	s_ashr_i32 s4, s0, 31
	v_and_b32_e32 v1, -16, v1
	v_sub_u32_e32 v0, v0, v2
	s_lshr_b32 s4, s4, 25
	v_add_u32_e32 v1, v13, v1
	v_ashrrev_i16_sdwa v0, v3, sext(v0) dst_sel:DWORD dst_unused:UNUSED_PAD src0_sel:DWORD src1_sel:BYTE_0
	v_and_b32_e32 v3, 3, v13
	s_add_i32 s4, s0, s4
	v_and_or_b32 v3, v1, s5, v3
	s_ashr_i32 s5, s4, 7
	s_and_b32 s4, s4, 0xffffff80
	s_sub_i32 s4, s0, s4
	s_bfe_i32 s0, s4, 0x80000
	s_bfe_u32 s0, s0, 0x3000c
	s_add_i32 s6, s4, s0
	s_bfe_i32 s0, s6, 0x80000
	s_and_b32 s6, s6, 0xf8
	s_sub_i32 s4, s4, s6
	s_lshl_b32 s5, s5, 3
	s_sext_i32_i16 s0, s0
	s_sext_i32_i8 s4, s4
	s_ashr_i32 s1, s8, 6
	s_lshr_b32 s0, s0, 3
	s_add_i32 s16, s5, s4
	s_ashr_i32 s17, s16, 31
	s_bfe_i64 s[6:7], s[0:1], 0x100000
	s_ashr_i32 s9, s8, 8
	s_lshl_b32 s53, s1, 10
	s_lshl_b64 s[4:5], s[16:17], 20
	s_lshl_b64 s[6:7], s[6:7], 20
	v_readlane_b32 s10, v254, 40
	s_add_u32 s48, s10, s6
	v_readlane_b32 s6, v254, 41
	v_lshlrev_b32_e32 v4, 5, v12
	v_bfe_i32 v14, v0, 0, 16
	v_lshlrev_b32_e32 v0, 1, v1
	v_lshrrev_b32_e32 v2, 2, v1
	s_addc_u32 s49, s6, s7
	s_add_i32 s17, s53, 0
	v_and_b32_e32 v4, 32, v4
	v_and_b32_e32 v0, 24, v0
	v_and_b32_e32 v2, 4, v2
	s_add_i32 m0, s17, 0x10000
	v_or3_b32 v0, v3, v2, v0
	v_add_lshl_u32 v2, v4, v14, 1
	global_load_lds_dwordx4 v130, s[48:49]
	s_add_i32 m0, s17, 0x12000
	v_lshl_add_u32 v134, v0, 12, v2
	v_add_u32_e32 v134, s101, v134
	v_add_u32_e32 v134, 0x40000, v134
	s_add_u32 s6, s48, 0x20000
	global_load_lds_dwordx4 v134, s[48:49]
	s_addc_u32 s7, s49, 0
	s_add_i32 m0, s17, 0x14000
	v_lshl_add_u32 v132, v1, 12, v2
	global_load_lds_dwordx4 v130, s[6:7]
	s_add_i32 m0, s17, 0x16000
	s_add_u32 s46, s33, s4
	s_addc_u32 s47, s52, s5
	s_add_i32 s54, s17, 0x2000
	global_load_lds_dwordx4 v134, s[6:7]
	s_mov_b32 m0, s17
	s_add_u32 s4, s46, 0x80000
	global_load_lds_dwordx4 v128, s[46:47]
	s_mov_b32 m0, s54
	s_addc_u32 s5, s47, 0
	s_add_i32 s55, s17, 0x4000
	global_load_lds_dwordx4 v132, s[46:47]
	s_mov_b32 m0, s55
	s_add_i32 s56, s17, 0x6000
	global_load_lds_dwordx4 v128, s[4:5]
	s_mov_b32 m0, s56
	v_mov_b32_e32 v131, 0
	global_load_lds_dwordx4 v132, s[4:5]
	v_mov_b32_e32 v135, v131
	v_mov_b32_e32 v129, v131
	v_mov_b32_e32 v133, v131
	s_cmp_eq_u32 s9, 1
	s_mov_b32 s57, 0
	v_lshl_add_u64 v[6:7], s[48:49], 0, v[130:131]
	v_lshl_add_u64 v[4:5], s[48:49], 0, v[134:135]
	v_lshl_add_u64 v[0:1], s[46:47], 0, v[128:129]
	s_cselect_b64 s[4:5], -1, 0
	s_cmp_lg_u32 s9, 1
	v_lshl_add_u64 v[2:3], s[46:47], 0, v[132:133]
	s_cbranch_scc1 .LBB0_511
	s_barrier
.LBB0_511:
	s_lshl_b32 s1, s1, 5
	s_mov_b64 s[6:7], 0x80
	s_and_b32 s1, s1, 0x60
	s_add_i32 m0, s17, 0x18000
	v_lshl_add_u64 v[6:7], v[6:7], 0, s[6:7]
	s_lshl_b32 s12, s9, 13
	s_lshl_b32 s13, s1, 7
	s_waitcnt vmcnt(2)
	s_barrier
	global_load_lds_dwordx4 v[6:7], off
	v_lshl_add_u64 v[4:5], v[4:5], 0, s[6:7]
	s_add_i32 m0, s17, 0x1a000
	s_add_i32 s58, s17, 0x8000
	s_add_i32 s59, s17, 0xa000
	global_load_lds_dwordx4 v[4:5], off
	v_lshl_add_u64 v[0:1], v[0:1], 0, s[6:7]
	s_mov_b32 m0, s58
	s_add_u32 s10, s48, 0x20080
	global_load_lds_dwordx4 v[0:1], off
	v_lshl_add_u64 v[0:1], v[2:3], 0, s[6:7]
	s_mov_b32 m0, s59
	s_addc_u32 s11, s49, 0
	global_load_lds_dwordx4 v[0:1], off
	s_add_i32 m0, s17, 0x1c000
	v_lshl_add_u64 v[0:1], s[10:11], 0, v[130:131]
	global_load_lds_dwordx4 v[0:1], off
	v_lshl_add_u64 v[0:1], s[10:11], 0, v[134:135]
	s_add_i32 m0, s17, 0x1e000
	s_cmpk_lt_u32 s8, 0x100
	global_load_lds_dwordx4 v[0:1], off
	v_lshrrev_b32_e32 v1, 1, v9
	v_and_b32_e32 v1, 24, v1
	v_and_b32_e32 v0, 15, v9
	v_lshlrev_b32_e32 v2, 1, v1
	v_lshl_or_b32 v146, s9, 6, v0
	v_lshl_or_b32 v0, v0, 6, v2
	v_lshlrev_b32_e32 v2, 2, v9
	v_and_b32_e32 v2, 32, v2
	v_bitop3_b32 v3, v0, s12, v2 bitop3:0xde
	v_bitop3_b32 v147, s13, v0, v2 bitop3:0xf6
	v_lshlrev_b32_e32 v0, 15, v8
	v_and_b32_e32 v0, 0xffff0000, v0
	v_or_b32_e32 v148, s1, v1
	v_lshl_add_u32 v0, v10, 12, v0
	v_and_b32_e32 v1, 1, v8
	v_lshl_or_b32 v0, v1, 6, v0
	v_lshl_add_u32 v136, v11, 1, v0
	v_lshlrev_b32_e32 v0, 15, v12
	v_and_b32_e32 v0, 0xffff0000, v0
	s_waitcnt vmcnt(6)
	v_lshl_add_u32 v0, v13, 12, v0
	v_and_b32_e32 v1, 1, v12
	s_cselect_b64 s[8:9], -1, 0
	v_lshl_or_b32 v0, v1, 6, v0
	s_add_i32 s61, 0, 0x10000
	s_add_i32 s62, 0, 0x14000
	s_sext_i32_i8 s63, s0
	s_ashr_i32 s60, s15, 31
	v_mov_b32_e32 v137, v131
	v_lshl_add_u32 v138, v14, 1, v0
	v_mov_b32_e32 v139, v131
	v_mov_b64_e32 v[140:141], 0x800
	v_mov_b64_e32 v[142:143], 0x7ff
	v_add_u32_e32 v149, s61, v147
	v_add_u32_e32 v150, s62, v147
	v_add_u32_e32 v151, 0, v3
	s_barrier
	s_waitcnt vmcnt(0)
	s_branch .LBB0_514

.Lmy_prio_skip1:
.LBB0_521:
	ds_read_b128 v[152:155], v149
	ds_read_b128 v[156:159], v149 offset:1024
	ds_read_b128 v[160:163], v149 offset:2048
	ds_read_b128 v[164:167], v149 offset:3072
	ds_read_b128 v[168:171], v150
	ds_read_b128 v[172:175], v150 offset:1024
	ds_read_b128 v[176:179], v150 offset:2048
	ds_read_b128 v[180:183], v150 offset:3072
	s_add_u32 s37, s46, 0xfff80080
	s_addc_u32 s38, s47, -1
	s_cmp_eq_u32 s36, 28
	s_cselect_b32 s51, s13, s38
	s_cselect_b32 s50, s64, s37
	s_cselect_b32 s49, s11, s35
	s_cselect_b32 s48, s65, s34
	s_add_i32 m0, s17, 0xc000
	ds_read_b128 v[184:187], v151
	ds_read_b128 v[188:191], v151 offset:1024
	ds_read_b128 v[192:195], v151 offset:2048
	ds_read_b128 v[196:199], v151 offset:3072
	ds_read_b128 v[200:203], v151 offset:4096
	ds_read_b128 v[204:207], v151 offset:5120
	ds_read_b128 v[208:211], v151 offset:6144
	ds_read_b128 v[212:215], v151 offset:7168
	global_load_lds_dwordx4 v136, s[46:47]
	s_add_i32 m0, s17, 0xe000
	s_nop 0
	global_load_lds_dwordx4 v138, s[46:47]
	s_waitcnt vmcnt(8)
	s_waitcnt lgkmcnt(0)
	s_barrier
	s_waitcnt lgkmcnt(0)
	v_mfma_f32_16x16x32_bf16 v[124:127], v[152:155], v[184:187], v[124:127]
	v_mfma_f32_16x16x32_bf16 v[120:123], v[160:163], v[184:187], v[120:123]
	v_mfma_f32_16x16x32_bf16 v[116:119], v[152:155], v[192:195], v[116:119]
	v_mfma_f32_16x16x32_bf16 v[108:111], v[160:163], v[192:195], v[108:111]
	v_mfma_f32_16x16x32_bf16 v[100:103], v[152:155], v[200:203], v[100:103]
	v_mfma_f32_16x16x32_bf16 v[92:95], v[160:163], v[200:203], v[92:95]
	v_mfma_f32_16x16x32_bf16 v[84:87], v[152:155], v[208:211], v[84:87]
	v_mfma_f32_16x16x32_bf16 v[76:79], v[160:163], v[208:211], v[76:79]
	v_mfma_f32_16x16x32_bf16 v[124:127], v[156:159], v[188:191], v[124:127]
	v_mfma_f32_16x16x32_bf16 v[120:123], v[164:167], v[188:191], v[120:123]
	v_mfma_f32_16x16x32_bf16 v[116:119], v[156:159], v[196:199], v[116:119]
	v_mfma_f32_16x16x32_bf16 v[108:111], v[164:167], v[196:199], v[108:111]
	v_mfma_f32_16x16x32_bf16 v[100:103], v[156:159], v[204:207], v[100:103]
	v_mfma_f32_16x16x32_bf16 v[92:95], v[164:167], v[204:207], v[92:95]
	v_mfma_f32_16x16x32_bf16 v[84:87], v[156:159], v[212:215], v[84:87]
	v_mfma_f32_16x16x32_bf16 v[76:79], v[164:167], v[212:215], v[76:79]
	v_mfma_f32_16x16x32_bf16 v[112:115], v[168:171], v[184:187], v[112:115]
	v_mfma_f32_16x16x32_bf16 v[104:107], v[176:179], v[184:187], v[104:107]
	v_mfma_f32_16x16x32_bf16 v[96:99], v[168:171], v[192:195], v[96:99]
	v_mfma_f32_16x16x32_bf16 v[88:91], v[176:179], v[192:195], v[88:91]
	v_mfma_f32_16x16x32_bf16 v[80:83], v[168:171], v[200:203], v[80:83]
	v_mfma_f32_16x16x32_bf16 v[72:75], v[176:179], v[200:203], v[72:75]
	v_mfma_f32_16x16x32_bf16 v[68:71], v[168:171], v[208:211], v[68:71]
	v_mfma_f32_16x16x32_bf16 v[64:67], v[176:179], v[208:211], v[64:67]
	v_mfma_f32_16x16x32_bf16 v[112:115], v[172:175], v[188:191], v[112:115]
	v_mfma_f32_16x16x32_bf16 v[104:107], v[180:183], v[188:191], v[104:107]
	v_mfma_f32_16x16x32_bf16 v[96:99], v[172:175], v[196:199], v[96:99]
	v_mfma_f32_16x16x32_bf16 v[88:91], v[180:183], v[196:199], v[88:91]
	v_mfma_f32_16x16x32_bf16 v[80:83], v[172:175], v[204:207], v[80:83]
	v_mfma_f32_16x16x32_bf16 v[72:75], v[180:183], v[204:207], v[72:75]
	v_mfma_f32_16x16x32_bf16 v[68:71], v[172:175], v[212:215], v[68:71]
	v_mfma_f32_16x16x32_bf16 v[64:67], v[180:183], v[212:215], v[64:67]
	s_barrier
	s_add_i32 s37, s61, s53
	s_mov_b32 m0, s37
	ds_read_b128 v[184:187], v151 offset:16384
	ds_read_b128 v[188:191], v151 offset:17408
	ds_read_b128 v[192:195], v151 offset:18432
	ds_read_b128 v[196:199], v151 offset:19456
	ds_read_b128 v[200:203], v151 offset:20480
	ds_read_b128 v[204:207], v151 offset:21504
	ds_read_b128 v[208:211], v151 offset:22528
	ds_read_b128 v[212:215], v151 offset:23552
	global_load_lds_dwordx4 v130, s[48:49]
	s_add_i32 m0, s37, 0x2000
	s_add_u32 s38, s48, 0x20000
	s_addc_u32 s39, s49, 0
	s_add_i32 s37, s62, s53
	global_load_lds_dwordx4 v134, s[48:49]
	s_mov_b32 m0, s37
	global_load_lds_dwordx4 v130, s[38:39]
	s_add_i32 m0, s37, 0x2000
	s_nop 0
	global_load_lds_dwordx4 v134, s[38:39]
	s_mov_b32 m0, s17
	s_nop 0
	global_load_lds_dwordx4 v128, s[50:51]
	s_mov_b32 m0, s54
	s_nop 0
	global_load_lds_dwordx4 v132, s[50:51]
	s_waitcnt vmcnt(8)
	s_waitcnt lgkmcnt(0)
	s_barrier
	s_waitcnt lgkmcnt(0)
	v_mfma_f32_16x16x32_bf16 v[60:63], v[152:155], v[184:187], v[60:63]
	v_mfma_f32_16x16x32_bf16 v[56:59], v[160:163], v[184:187], v[56:59]
	v_mfma_f32_16x16x32_bf16 v[52:55], v[152:155], v[192:195], v[52:55]
	v_mfma_f32_16x16x32_bf16 v[44:47], v[160:163], v[192:195], v[44:47]
	v_mfma_f32_16x16x32_bf16 v[36:39], v[152:155], v[200:203], v[36:39]
	v_mfma_f32_16x16x32_bf16 v[28:31], v[160:163], v[200:203], v[28:31]
	v_mfma_f32_16x16x32_bf16 v[20:23], v[152:155], v[208:211], v[20:23]
	v_mfma_f32_16x16x32_bf16 v[12:15], v[160:163], v[208:211], v[12:15]
	v_mfma_f32_16x16x32_bf16 v[60:63], v[156:159], v[188:191], v[60:63]
	v_mfma_f32_16x16x32_bf16 v[56:59], v[164:167], v[188:191], v[56:59]
	v_mfma_f32_16x16x32_bf16 v[52:55], v[156:159], v[196:199], v[52:55]
	v_mfma_f32_16x16x32_bf16 v[44:47], v[164:167], v[196:199], v[44:47]
	v_mfma_f32_16x16x32_bf16 v[36:39], v[156:159], v[204:207], v[36:39]
	v_mfma_f32_16x16x32_bf16 v[28:31], v[164:167], v[204:207], v[28:31]
	v_mfma_f32_16x16x32_bf16 v[20:23], v[156:159], v[212:215], v[20:23]
	v_mfma_f32_16x16x32_bf16 v[12:15], v[164:167], v[212:215], v[12:15]
	v_mfma_f32_16x16x32_bf16 v[48:51], v[168:171], v[184:187], v[48:51]
	v_mfma_f32_16x16x32_bf16 v[40:43], v[176:179], v[184:187], v[40:43]
	v_mfma_f32_16x16x32_bf16 v[32:35], v[168:171], v[192:195], v[32:35]
	v_mfma_f32_16x16x32_bf16 v[24:27], v[176:179], v[192:195], v[24:27]
	v_mfma_f32_16x16x32_bf16 v[16:19], v[168:171], v[200:203], v[16:19]
	v_mfma_f32_16x16x32_bf16 v[8:11], v[176:179], v[200:203], v[8:11]
	v_mfma_f32_16x16x32_bf16 v[4:7], v[168:171], v[208:211], v[4:7]
	v_mfma_f32_16x16x32_bf16 v[0:3], v[176:179], v[208:211], v[0:3]
	v_mfma_f32_16x16x32_bf16 v[48:51], v[172:175], v[188:191], v[48:51]
	v_mfma_f32_16x16x32_bf16 v[40:43], v[180:183], v[188:191], v[40:43]
	v_mfma_f32_16x16x32_bf16 v[32:35], v[172:175], v[196:199], v[32:35]
	v_mfma_f32_16x16x32_bf16 v[24:27], v[180:183], v[196:199], v[24:27]
	v_mfma_f32_16x16x32_bf16 v[16:19], v[172:175], v[204:207], v[16:19]
	v_mfma_f32_16x16x32_bf16 v[8:11], v[180:183], v[204:207], v[8:11]
	v_mfma_f32_16x16x32_bf16 v[4:7], v[172:175], v[212:215], v[4:7]
	v_mfma_f32_16x16x32_bf16 v[0:3], v[180:183], v[212:215], v[0:3]
	s_barrier
	s_add_i32 s37, 0, 0x18000
	s_add_i32 s40, 0, 0x1c000
	v_add_u32_e32 v164, s37, v147
	v_add_u32_e32 v180, s40, v147
	ds_read_b128 v[152:155], v164
	ds_read_b128 v[156:159], v164 offset:1024
	ds_read_b128 v[160:163], v164 offset:2048
	ds_read_b128 v[164:167], v164 offset:3072
	ds_read_b128 v[168:171], v180
	ds_read_b128 v[172:175], v180 offset:1024
	ds_read_b128 v[176:179], v180 offset:2048
	ds_read_b128 v[180:183], v180 offset:3072
	s_add_u32 s38, s50, 0x80000
	s_addc_u32 s39, s51, 0
	s_mov_b32 m0, s55
	ds_read_b128 v[184:187], v151 offset:32768
	ds_read_b128 v[188:191], v151 offset:33792
	ds_read_b128 v[192:195], v151 offset:34816
	ds_read_b128 v[196:199], v151 offset:35840
	ds_read_b128 v[200:203], v151 offset:36864
	ds_read_b128 v[204:207], v151 offset:37888
	ds_read_b128 v[208:211], v151 offset:38912
	ds_read_b128 v[212:215], v151 offset:39936
	global_load_lds_dwordx4 v128, s[38:39]
	s_mov_b32 m0, s56
	s_nop 0
	global_load_lds_dwordx4 v132, s[38:39]
	s_waitcnt vmcnt(8)
	s_waitcnt lgkmcnt(0)
	s_barrier
	s_waitcnt lgkmcnt(0)
	v_mfma_f32_16x16x32_bf16 v[124:127], v[152:155], v[184:187], v[124:127]
	v_mfma_f32_16x16x32_bf16 v[120:123], v[160:163], v[184:187], v[120:123]
	v_mfma_f32_16x16x32_bf16 v[116:119], v[152:155], v[192:195], v[116:119]
	v_mfma_f32_16x16x32_bf16 v[108:111], v[160:163], v[192:195], v[108:111]
	v_mfma_f32_16x16x32_bf16 v[100:103], v[152:155], v[200:203], v[100:103]
	v_mfma_f32_16x16x32_bf16 v[92:95], v[160:163], v[200:203], v[92:95]
	v_mfma_f32_16x16x32_bf16 v[84:87], v[152:155], v[208:211], v[84:87]
	v_mfma_f32_16x16x32_bf16 v[76:79], v[160:163], v[208:211], v[76:79]
	v_mfma_f32_16x16x32_bf16 v[124:127], v[156:159], v[188:191], v[124:127]
	v_mfma_f32_16x16x32_bf16 v[120:123], v[164:167], v[188:191], v[120:123]
	v_mfma_f32_16x16x32_bf16 v[116:119], v[156:159], v[196:199], v[116:119]
	v_mfma_f32_16x16x32_bf16 v[108:111], v[164:167], v[196:199], v[108:111]
	v_mfma_f32_16x16x32_bf16 v[100:103], v[156:159], v[204:207], v[100:103]
	v_mfma_f32_16x16x32_bf16 v[92:95], v[164:167], v[204:207], v[92:95]
	v_mfma_f32_16x16x32_bf16 v[84:87], v[156:159], v[212:215], v[84:87]
	v_mfma_f32_16x16x32_bf16 v[76:79], v[164:167], v[212:215], v[76:79]
	v_mfma_f32_16x16x32_bf16 v[112:115], v[168:171], v[184:187], v[112:115]
	v_mfma_f32_16x16x32_bf16 v[104:107], v[176:179], v[184:187], v[104:107]
	v_mfma_f32_16x16x32_bf16 v[96:99], v[168:171], v[192:195], v[96:99]
	v_mfma_f32_16x16x32_bf16 v[88:91], v[176:179], v[192:195], v[88:91]
	v_mfma_f32_16x16x32_bf16 v[80:83], v[168:171], v[200:203], v[80:83]
	v_mfma_f32_16x16x32_bf16 v[72:75], v[176:179], v[200:203], v[72:75]
	v_mfma_f32_16x16x32_bf16 v[68:71], v[168:171], v[208:211], v[68:71]
	v_mfma_f32_16x16x32_bf16 v[64:67], v[176:179], v[208:211], v[64:67]
	v_mfma_f32_16x16x32_bf16 v[112:115], v[172:175], v[188:191], v[112:115]
	v_mfma_f32_16x16x32_bf16 v[104:107], v[180:183], v[188:191], v[104:107]
	v_mfma_f32_16x16x32_bf16 v[96:99], v[172:175], v[196:199], v[96:99]
	v_mfma_f32_16x16x32_bf16 v[88:91], v[180:183], v[196:199], v[88:91]
	v_mfma_f32_16x16x32_bf16 v[80:83], v[172:175], v[204:207], v[80:83]
	v_mfma_f32_16x16x32_bf16 v[72:75], v[180:183], v[204:207], v[72:75]
	v_mfma_f32_16x16x32_bf16 v[68:71], v[172:175], v[212:215], v[68:71]
	v_mfma_f32_16x16x32_bf16 v[64:67], v[180:183], v[212:215], v[64:67]
	s_barrier
	s_add_i32 s37, s37, s53
	s_mov_b32 m0, s37
	ds_read_b128 v[184:187], v151 offset:49152
	ds_read_b128 v[188:191], v151 offset:50176
	ds_read_b128 v[192:195], v151 offset:51200
	ds_read_b128 v[196:199], v151 offset:52224
	ds_read_b128 v[200:203], v151 offset:53248
	ds_read_b128 v[204:207], v151 offset:54272
	ds_read_b128 v[208:211], v151 offset:55296
	ds_read_b128 v[212:215], v151 offset:56320
	s_add_u32 s100, s48, 0x80
	s_addc_u32 s101, s49, 0
	global_load_lds_dwordx4 v130, s[100:101]
	s_add_i32 m0, s37, 0x2000
	s_add_u32 s38, s48, 0x20080
	s_addc_u32 s39, s49, 0
	s_add_i32 s37, s40, s53
	s_add_u32 s100, s48, 0x80
	s_addc_u32 s101, s49, 0
	global_load_lds_dwordx4 v134, s[100:101]
	s_mov_b32 m0, s37
	s_nop 0
	global_load_lds_dwordx4 v130, s[38:39]
	s_add_i32 m0, s37, 0x2000
	s_nop 0
	global_load_lds_dwordx4 v134, s[38:39]
	s_mov_b32 m0, s58
	s_nop 0
	s_add_u32 s100, s50, 0x80
	s_addc_u32 s101, s51, 0
	global_load_lds_dwordx4 v128, s[100:101]
	s_mov_b32 m0, s59
	s_nop 0
	s_add_u32 s100, s50, 0x80
	s_addc_u32 s101, s51, 0
	global_load_lds_dwordx4 v132, s[100:101]
	s_waitcnt vmcnt(8)
	s_waitcnt lgkmcnt(0)
	s_barrier
	s_waitcnt lgkmcnt(0)
	v_mfma_f32_16x16x32_bf16 v[60:63], v[152:155], v[184:187], v[60:63]
	v_mfma_f32_16x16x32_bf16 v[56:59], v[160:163], v[184:187], v[56:59]
	v_mfma_f32_16x16x32_bf16 v[52:55], v[152:155], v[192:195], v[52:55]
	v_mfma_f32_16x16x32_bf16 v[44:47], v[160:163], v[192:195], v[44:47]
	v_mfma_f32_16x16x32_bf16 v[36:39], v[152:155], v[200:203], v[36:39]
	v_mfma_f32_16x16x32_bf16 v[28:31], v[160:163], v[200:203], v[28:31]
	v_mfma_f32_16x16x32_bf16 v[20:23], v[152:155], v[208:211], v[20:23]
	v_mfma_f32_16x16x32_bf16 v[12:15], v[160:163], v[208:211], v[12:15]
	v_mfma_f32_16x16x32_bf16 v[60:63], v[156:159], v[188:191], v[60:63]
	v_mfma_f32_16x16x32_bf16 v[56:59], v[164:167], v[188:191], v[56:59]
	v_mfma_f32_16x16x32_bf16 v[52:55], v[156:159], v[196:199], v[52:55]
	v_mfma_f32_16x16x32_bf16 v[44:47], v[164:167], v[196:199], v[44:47]
	v_mfma_f32_16x16x32_bf16 v[36:39], v[156:159], v[204:207], v[36:39]
	v_mfma_f32_16x16x32_bf16 v[28:31], v[164:167], v[204:207], v[28:31]
	v_mfma_f32_16x16x32_bf16 v[20:23], v[156:159], v[212:215], v[20:23]
	v_mfma_f32_16x16x32_bf16 v[12:15], v[164:167], v[212:215], v[12:15]
	v_mfma_f32_16x16x32_bf16 v[48:51], v[168:171], v[184:187], v[48:51]
	v_mfma_f32_16x16x32_bf16 v[40:43], v[176:179], v[184:187], v[40:43]
	v_mfma_f32_16x16x32_bf16 v[32:35], v[168:171], v[192:195], v[32:35]
	v_mfma_f32_16x16x32_bf16 v[24:27], v[176:179], v[192:195], v[24:27]
	v_mfma_f32_16x16x32_bf16 v[16:19], v[168:171], v[200:203], v[16:19]
	v_mfma_f32_16x16x32_bf16 v[8:11], v[176:179], v[200:203], v[8:11]
	v_mfma_f32_16x16x32_bf16 v[4:7], v[168:171], v[208:211], v[4:7]
	v_mfma_f32_16x16x32_bf16 v[0:3], v[176:179], v[208:211], v[0:3]
	v_mfma_f32_16x16x32_bf16 v[48:51], v[172:175], v[188:191], v[48:51]
	v_mfma_f32_16x16x32_bf16 v[40:43], v[180:183], v[188:191], v[40:43]
	v_mfma_f32_16x16x32_bf16 v[32:35], v[172:175], v[196:199], v[32:35]
	v_mfma_f32_16x16x32_bf16 v[24:27], v[180:183], v[196:199], v[24:27]
	v_mfma_f32_16x16x32_bf16 v[16:19], v[172:175], v[204:207], v[16:19]
	v_mfma_f32_16x16x32_bf16 v[8:11], v[180:183], v[204:207], v[8:11]
	v_mfma_f32_16x16x32_bf16 v[4:7], v[172:175], v[212:215], v[4:7]
	v_mfma_f32_16x16x32_bf16 v[0:3], v[180:183], v[212:215], v[0:3]
	s_barrier
	s_add_i32 s36, s36, 2
	s_add_u32 s46, s46, 0x100
	s_addc_u32 s47, s47, 0
	s_add_u32 s34, s34, 0x100
	s_addc_u32 s35, s35, 0
	s_cmp_gt_u32 s36, 29
	s_cbranch_scc0 .LBB0_521
	s_setprio 0
	s_and_b64 vcc, exec, s[8:9]
	s_cbranch_vccz .LBB0_524
	s_barrier
.LBB0_524:
	v_and_b32_e32 v152, 0xfffffff7, v146
	v_lshl_add_u32 v152, s16, 8, v152
	v_and_b32_e32 v153, 0x60, v148
	v_add_u32_e32 v153, v153, v148
	v_lshl_or_b32 v153, s63, 8, v153
	v_bfe_u32 v154, v146, 3, 1
	v_lshlrev_b32_e32 v152, 13, v152
	v_lshl_add_u32 v152, v153, 1, v152
	v_lshl_add_u32 v152, v154, 6, v152
	v_cvt_pk_bf16_f32 v124, v124, v125
	v_cvt_pk_bf16_f32 v125, v126, v127
	v_cvt_pk_bf16_f32 v126, v120, v121
	v_cvt_pk_bf16_f32 v127, v122, v123
	v_cvt_pk_bf16_f32 v112, v112, v113
	v_cvt_pk_bf16_f32 v113, v114, v115
	v_cvt_pk_bf16_f32 v114, v104, v105
	v_cvt_pk_bf16_f32 v115, v106, v107
	s_add_u32 s100, s74, 0x0
	s_addc_u32 s101, s75, 0
	v_mov_b32_dpp v120, v124 row_ror:8 row_mask:0xf bank_mask:0xf
	v_mov_b32_dpp v121, v125 row_ror:8 row_mask:0xf bank_mask:0xf
	v_mov_b32_dpp v122, v126 row_ror:8 row_mask:0xf bank_mask:0xf
	v_mov_b32_dpp v123, v127 row_ror:8 row_mask:0xf bank_mask:0xf
	v_mov_b32_dpp v124, v112 row_ror:8 row_mask:0xf bank_mask:0xc
	v_mov_b32_dpp v125, v113 row_ror:8 row_mask:0xf bank_mask:0xc
	v_mov_b32_dpp v126, v114 row_ror:8 row_mask:0xf bank_mask:0xc
	v_mov_b32_dpp v127, v115 row_ror:8 row_mask:0xf bank_mask:0xc
	v_mov_b32_dpp v112, v120 quad_perm:[0,1,2,3] row_mask:0xf bank_mask:0x3
	v_mov_b32_dpp v113, v121 quad_perm:[0,1,2,3] row_mask:0xf bank_mask:0x3
	v_mov_b32_dpp v114, v122 quad_perm:[0,1,2,3] row_mask:0xf bank_mask:0x3
	v_mov_b32_dpp v115, v123 quad_perm:[0,1,2,3] row_mask:0xf bank_mask:0x3
	global_store_dwordx4 v152, v[124:127], s[100:101]
	s_add_u32 s100, s100, 0x10000
	s_addc_u32 s101, s101, 0
	global_store_dwordx4 v152, v[112:115], s[100:101]
	v_cvt_pk_bf16_f32 v116, v116, v117
	v_cvt_pk_bf16_f32 v117, v118, v119
	v_cvt_pk_bf16_f32 v118, v108, v109
	v_cvt_pk_bf16_f32 v119, v110, v111
	v_cvt_pk_bf16_f32 v96, v96, v97
	v_cvt_pk_bf16_f32 v97, v98, v99
	v_cvt_pk_bf16_f32 v98, v88, v89
	v_cvt_pk_bf16_f32 v99, v90, v91
	s_add_u32 s100, s74, 0x20000
	s_addc_u32 s101, s75, 0
	v_mov_b32_dpp v108, v116 row_ror:8 row_mask:0xf bank_mask:0xf
	v_mov_b32_dpp v109, v117 row_ror:8 row_mask:0xf bank_mask:0xf
	v_mov_b32_dpp v110, v118 row_ror:8 row_mask:0xf bank_mask:0xf
	v_mov_b32_dpp v111, v119 row_ror:8 row_mask:0xf bank_mask:0xf
	v_mov_b32_dpp v116, v96 row_ror:8 row_mask:0xf bank_mask:0xc
	v_mov_b32_dpp v117, v97 row_ror:8 row_mask:0xf bank_mask:0xc
	v_mov_b32_dpp v118, v98 row_ror:8 row_mask:0xf bank_mask:0xc
	v_mov_b32_dpp v119, v99 row_ror:8 row_mask:0xf bank_mask:0xc
	v_mov_b32_dpp v96, v108 quad_perm:[0,1,2,3] row_mask:0xf bank_mask:0x3
	v_mov_b32_dpp v97, v109 quad_perm:[0,1,2,3] row_mask:0xf bank_mask:0x3
	v_mov_b32_dpp v98, v110 quad_perm:[0,1,2,3] row_mask:0xf bank_mask:0x3
	v_mov_b32_dpp v99, v111 quad_perm:[0,1,2,3] row_mask:0xf bank_mask:0x3
	global_store_dwordx4 v152, v[116:119], s[100:101]
	s_add_u32 s100, s100, 0x10000
	s_addc_u32 s101, s101, 0
	global_store_dwordx4 v152, v[96:99], s[100:101]
	v_cvt_pk_bf16_f32 v100, v100, v101
	v_cvt_pk_bf16_f32 v101, v102, v103
	v_cvt_pk_bf16_f32 v102, v92, v93
	v_cvt_pk_bf16_f32 v103, v94, v95
	v_cvt_pk_bf16_f32 v80, v80, v81
	v_cvt_pk_bf16_f32 v81, v82, v83
	v_cvt_pk_bf16_f32 v82, v72, v73
	v_cvt_pk_bf16_f32 v83, v74, v75
	s_add_u32 s100, s74, 0x40000
	s_addc_u32 s101, s75, 0
	v_mov_b32_dpp v92, v100 row_ror:8 row_mask:0xf bank_mask:0xf
	v_mov_b32_dpp v93, v101 row_ror:8 row_mask:0xf bank_mask:0xf
	v_mov_b32_dpp v94, v102 row_ror:8 row_mask:0xf bank_mask:0xf
	v_mov_b32_dpp v95, v103 row_ror:8 row_mask:0xf bank_mask:0xf
	v_mov_b32_dpp v100, v80 row_ror:8 row_mask:0xf bank_mask:0xc
	v_mov_b32_dpp v101, v81 row_ror:8 row_mask:0xf bank_mask:0xc
	v_mov_b32_dpp v102, v82 row_ror:8 row_mask:0xf bank_mask:0xc
	v_mov_b32_dpp v103, v83 row_ror:8 row_mask:0xf bank_mask:0xc
	v_mov_b32_dpp v80, v92 quad_perm:[0,1,2,3] row_mask:0xf bank_mask:0x3
	v_mov_b32_dpp v81, v93 quad_perm:[0,1,2,3] row_mask:0xf bank_mask:0x3
	v_mov_b32_dpp v82, v94 quad_perm:[0,1,2,3] row_mask:0xf bank_mask:0x3
	v_mov_b32_dpp v83, v95 quad_perm:[0,1,2,3] row_mask:0xf bank_mask:0x3
	global_store_dwordx4 v152, v[100:103], s[100:101]
	s_add_u32 s100, s100, 0x10000
	s_addc_u32 s101, s101, 0
	global_store_dwordx4 v152, v[80:83], s[100:101]
	v_cvt_pk_bf16_f32 v84, v84, v85
	v_cvt_pk_bf16_f32 v85, v86, v87
	v_cvt_pk_bf16_f32 v86, v76, v77
	v_cvt_pk_bf16_f32 v87, v78, v79
	v_cvt_pk_bf16_f32 v68, v68, v69
	v_cvt_pk_bf16_f32 v69, v70, v71
	v_cvt_pk_bf16_f32 v70, v64, v65
	v_cvt_pk_bf16_f32 v71, v66, v67
	s_add_u32 s100, s74, 0x60000
	s_addc_u32 s101, s75, 0
	v_mov_b32_dpp v76, v84 row_ror:8 row_mask:0xf bank_mask:0xf
	v_mov_b32_dpp v77, v85 row_ror:8 row_mask:0xf bank_mask:0xf
	v_mov_b32_dpp v78, v86 row_ror:8 row_mask:0xf bank_mask:0xf
	v_mov_b32_dpp v79, v87 row_ror:8 row_mask:0xf bank_mask:0xf
	v_mov_b32_dpp v84, v68 row_ror:8 row_mask:0xf bank_mask:0xc
	v_mov_b32_dpp v85, v69 row_ror:8 row_mask:0xf bank_mask:0xc
	v_mov_b32_dpp v86, v70 row_ror:8 row_mask:0xf bank_mask:0xc
	v_mov_b32_dpp v87, v71 row_ror:8 row_mask:0xf bank_mask:0xc
	v_mov_b32_dpp v68, v76 quad_perm:[0,1,2,3] row_mask:0xf bank_mask:0x3
	v_mov_b32_dpp v69, v77 quad_perm:[0,1,2,3] row_mask:0xf bank_mask:0x3
	v_mov_b32_dpp v70, v78 quad_perm:[0,1,2,3] row_mask:0xf bank_mask:0x3
	v_mov_b32_dpp v71, v79 quad_perm:[0,1,2,3] row_mask:0xf bank_mask:0x3
	global_store_dwordx4 v152, v[84:87], s[100:101]
	s_add_u32 s100, s100, 0x10000
	s_addc_u32 s101, s101, 0
	global_store_dwordx4 v152, v[68:71], s[100:101]
	v_cvt_pk_bf16_f32 v60, v60, v61
	v_cvt_pk_bf16_f32 v61, v62, v63
	v_cvt_pk_bf16_f32 v62, v56, v57
	v_cvt_pk_bf16_f32 v63, v58, v59
	v_cvt_pk_bf16_f32 v48, v48, v49
	v_cvt_pk_bf16_f32 v49, v50, v51
	v_cvt_pk_bf16_f32 v50, v40, v41
	v_cvt_pk_bf16_f32 v51, v42, v43
	s_add_u32 s100, s74, 0x100000
	s_addc_u32 s101, s75, 0
	v_mov_b32_dpp v56, v60 row_ror:8 row_mask:0xf bank_mask:0xf
	v_mov_b32_dpp v57, v61 row_ror:8 row_mask:0xf bank_mask:0xf
	v_mov_b32_dpp v58, v62 row_ror:8 row_mask:0xf bank_mask:0xf
	v_mov_b32_dpp v59, v63 row_ror:8 row_mask:0xf bank_mask:0xf
	v_mov_b32_dpp v60, v48 row_ror:8 row_mask:0xf bank_mask:0xc
	v_mov_b32_dpp v61, v49 row_ror:8 row_mask:0xf bank_mask:0xc
	v_mov_b32_dpp v62, v50 row_ror:8 row_mask:0xf bank_mask:0xc
	v_mov_b32_dpp v63, v51 row_ror:8 row_mask:0xf bank_mask:0xc
	v_mov_b32_dpp v48, v56 quad_perm:[0,1,2,3] row_mask:0xf bank_mask:0x3
	v_mov_b32_dpp v49, v57 quad_perm:[0,1,2,3] row_mask:0xf bank_mask:0x3
	v_mov_b32_dpp v50, v58 quad_perm:[0,1,2,3] row_mask:0xf bank_mask:0x3
	v_mov_b32_dpp v51, v59 quad_perm:[0,1,2,3] row_mask:0xf bank_mask:0x3
	global_store_dwordx4 v152, v[60:63], s[100:101]
	s_add_u32 s100, s100, 0x10000
	s_addc_u32 s101, s101, 0
	global_store_dwordx4 v152, v[48:51], s[100:101]
	v_cvt_pk_bf16_f32 v52, v52, v53
	v_cvt_pk_bf16_f32 v53, v54, v55
	v_cvt_pk_bf16_f32 v54, v44, v45
	v_cvt_pk_bf16_f32 v55, v46, v47
	v_cvt_pk_bf16_f32 v32, v32, v33
	v_cvt_pk_bf16_f32 v33, v34, v35
	v_cvt_pk_bf16_f32 v34, v24, v25
	v_cvt_pk_bf16_f32 v35, v26, v27
	s_add_u32 s100, s74, 0x120000
	s_addc_u32 s101, s75, 0
	v_mov_b32_dpp v44, v52 row_ror:8 row_mask:0xf bank_mask:0xf
	v_mov_b32_dpp v45, v53 row_ror:8 row_mask:0xf bank_mask:0xf
	v_mov_b32_dpp v46, v54 row_ror:8 row_mask:0xf bank_mask:0xf
	v_mov_b32_dpp v47, v55 row_ror:8 row_mask:0xf bank_mask:0xf
	v_mov_b32_dpp v52, v32 row_ror:8 row_mask:0xf bank_mask:0xc
	v_mov_b32_dpp v53, v33 row_ror:8 row_mask:0xf bank_mask:0xc
	v_mov_b32_dpp v54, v34 row_ror:8 row_mask:0xf bank_mask:0xc
	v_mov_b32_dpp v55, v35 row_ror:8 row_mask:0xf bank_mask:0xc
	v_mov_b32_dpp v32, v44 quad_perm:[0,1,2,3] row_mask:0xf bank_mask:0x3
	v_mov_b32_dpp v33, v45 quad_perm:[0,1,2,3] row_mask:0xf bank_mask:0x3
	v_mov_b32_dpp v34, v46 quad_perm:[0,1,2,3] row_mask:0xf bank_mask:0x3
	v_mov_b32_dpp v35, v47 quad_perm:[0,1,2,3] row_mask:0xf bank_mask:0x3
	global_store_dwordx4 v152, v[52:55], s[100:101]
	s_add_u32 s100, s100, 0x10000
	s_addc_u32 s101, s101, 0
	global_store_dwordx4 v152, v[32:35], s[100:101]
	v_cvt_pk_bf16_f32 v36, v36, v37
	v_cvt_pk_bf16_f32 v37, v38, v39
	v_cvt_pk_bf16_f32 v38, v28, v29
	v_cvt_pk_bf16_f32 v39, v30, v31
	v_cvt_pk_bf16_f32 v16, v16, v17
	v_cvt_pk_bf16_f32 v17, v18, v19
	v_cvt_pk_bf16_f32 v18, v8, v9
	v_cvt_pk_bf16_f32 v19, v10, v11
	s_add_u32 s100, s74, 0x140000
	s_addc_u32 s101, s75, 0
	v_mov_b32_dpp v28, v36 row_ror:8 row_mask:0xf bank_mask:0xf
	v_mov_b32_dpp v29, v37 row_ror:8 row_mask:0xf bank_mask:0xf
	v_mov_b32_dpp v30, v38 row_ror:8 row_mask:0xf bank_mask:0xf
	v_mov_b32_dpp v31, v39 row_ror:8 row_mask:0xf bank_mask:0xf
	v_mov_b32_dpp v36, v16 row_ror:8 row_mask:0xf bank_mask:0xc
	v_mov_b32_dpp v37, v17 row_ror:8 row_mask:0xf bank_mask:0xc
	v_mov_b32_dpp v38, v18 row_ror:8 row_mask:0xf bank_mask:0xc
	v_mov_b32_dpp v39, v19 row_ror:8 row_mask:0xf bank_mask:0xc
	v_mov_b32_dpp v16, v28 quad_perm:[0,1,2,3] row_mask:0xf bank_mask:0x3
	v_mov_b32_dpp v17, v29 quad_perm:[0,1,2,3] row_mask:0xf bank_mask:0x3
	v_mov_b32_dpp v18, v30 quad_perm:[0,1,2,3] row_mask:0xf bank_mask:0x3
	v_mov_b32_dpp v19, v31 quad_perm:[0,1,2,3] row_mask:0xf bank_mask:0x3
	global_store_dwordx4 v152, v[36:39], s[100:101]
	s_add_u32 s100, s100, 0x10000
	s_addc_u32 s101, s101, 0
	global_store_dwordx4 v152, v[16:19], s[100:101]
	v_cvt_pk_bf16_f32 v20, v20, v21
	v_cvt_pk_bf16_f32 v21, v22, v23
	v_cvt_pk_bf16_f32 v22, v12, v13
	v_cvt_pk_bf16_f32 v23, v14, v15
	v_cvt_pk_bf16_f32 v4, v4, v5
	v_cvt_pk_bf16_f32 v5, v6, v7
	v_cvt_pk_bf16_f32 v6, v0, v1
	v_cvt_pk_bf16_f32 v7, v2, v3
	s_add_u32 s100, s74, 0x160000
	s_addc_u32 s101, s75, 0
	v_mov_b32_dpp v12, v20 row_ror:8 row_mask:0xf bank_mask:0xf
	v_mov_b32_dpp v13, v21 row_ror:8 row_mask:0xf bank_mask:0xf
	v_mov_b32_dpp v14, v22 row_ror:8 row_mask:0xf bank_mask:0xf
	v_mov_b32_dpp v15, v23 row_ror:8 row_mask:0xf bank_mask:0xf
	v_mov_b32_dpp v20, v4 row_ror:8 row_mask:0xf bank_mask:0xc
	v_mov_b32_dpp v21, v5 row_ror:8 row_mask:0xf bank_mask:0xc
	v_mov_b32_dpp v22, v6 row_ror:8 row_mask:0xf bank_mask:0xc
	v_mov_b32_dpp v23, v7 row_ror:8 row_mask:0xf bank_mask:0xc
	v_mov_b32_dpp v4, v12 quad_perm:[0,1,2,3] row_mask:0xf bank_mask:0x3
	v_mov_b32_dpp v5, v13 quad_perm:[0,1,2,3] row_mask:0xf bank_mask:0x3
	v_mov_b32_dpp v6, v14 quad_perm:[0,1,2,3] row_mask:0xf bank_mask:0x3
	v_mov_b32_dpp v7, v15 quad_perm:[0,1,2,3] row_mask:0xf bank_mask:0x3
	global_store_dwordx4 v152, v[20:23], s[100:101]
	s_add_u32 s100, s100, 0x10000
	s_addc_u32 s101, s101, 0
	global_store_dwordx4 v152, v[4:7], s[100:101]
	s_andn2_b64 vcc, exec, s[0:1]
	s_mov_b64 s[0:1], -1
	s_cbranch_vccnz .LBB0_513
	s_andn2_b64 vcc, exec, s[4:5]
	s_cbranch_vccnz .LBB0_512
	s_barrier
	s_branch .LBB0_512

.LBB0_582:
	v_readlane_b32 s4, v254, 1
	s_cmp_lt_i32 s4, 8
	s_cselect_b64 s[2:3], -1, 0
	s_and_b64 s[2:3], s[2:3], s[0:1]
	s_andn2_b64 vcc, exec, s[2:3]
	v_readlane_b32 s5, v254, 2
	v_readlane_b32 s6, v254, 3
	v_readlane_b32 s7, v254, 4
	s_cbranch_vccnz .LBB0_607
	s_bfe_u32 s101, s97, 0x10008
	s_lshl_b32 s101, s101, 18
	v_mbcnt_lo_u32_b32 v9, -1, 0
	v_mbcnt_hi_u32_b32 v9, -1, v9
	s_cmpk_gt_i32 s96, 0x7ff
	v_add_u32_e32 v224, s97, v9
	s_nop 0
	v_readfirstlane_b32 s10, v224
	s_cbranch_scc1 .LBB0_607
	s_ashr_i32 s14, s96, 31
	s_lshr_b32 s0, s14, 29
	s_add_i32 s5, s96, s0
	s_and_b32 s0, s5, -8
	s_sub_i32 s6, s96, s0
	s_cmp_gt_i32 s6, -1
	s_cbranch_scc0 .LBB0_586
	s_lshl_b32 s4, s6, 8
	s_cbranch_execz .LBB0_587
	s_branch .LBB0_588

.LBB0_588:
	v_ashrrev_i32_e32 v1, 31, v224
	v_lshrrev_b32_e32 v1, 26, v1
	v_add_u32_e32 v1, v224, v1
	v_ashrrev_i32_e32 v8, 6, v1
	v_bfe_i32 v1, v224, 27, 1
	v_lshlrev_b32_e32 v0, 4, v224
	v_lshrrev_b32_e32 v1, 22, v1
	v_add_u32_e32 v1, v0, v1
	v_and_b32_e32 v1, 0xfffffc00, v1
	v_sub_u32_e32 v1, v0, v1
	v_lshrrev_b32_e32 v2, 4, v1
	v_bitop3_b32 v1, v2, v1, 32 bitop3:0x6c
	v_ashrrev_i32_e32 v3, 31, v1
	v_lshrrev_b32_e32 v3, 26, v3
	v_add_u32_e32 v3, v1, v3
	v_lshlrev_b32_e32 v2, 3, v8
	v_ashrrev_i32_e32 v10, 6, v3
	v_and_b32_e32 v3, 0xc0, v3
	v_and_b32_e32 v2, -16, v2
	v_sub_u32_e32 v1, v1, v3
	v_mov_b32_e32 v3, 1
	v_add_u32_e32 v2, v10, v2
	v_ashrrev_i16_sdwa v1, v3, sext(v1) dst_sel:DWORD dst_unused:UNUSED_PAD src0_sel:DWORD src1_sel:BYTE_0
	s_ashr_i32 s0, s5, 3
	v_lshlrev_b32_e32 v4, 5, v8
	v_bfe_i32 v11, v1, 0, 16
	v_lshlrev_b32_e32 v1, 1, v2
	v_lshrrev_b32_e32 v5, 2, v2
	v_and_b32_e32 v6, 3, v10
	s_mov_b32 s5, 0x7ffe0
	v_and_b32_e32 v4, 32, v4
	v_and_b32_e32 v1, 24, v1
	v_and_b32_e32 v5, 4, v5
	v_and_or_b32 v6, v2, s5, v6
	v_or3_b32 v1, v6, v5, v1
	v_add_lshl_u32 v4, v4, v11, 1
	v_add_u32_e32 v0, 0x2000, v0
	v_lshl_add_u32 v130, v1, 13, v4
	v_add_u32_e32 v130, s101, v130
	v_ashrrev_i32_e32 v1, 31, v0
	v_lshrrev_b32_e32 v1, 22, v1
	v_add_u32_e32 v1, v0, v1
	v_ashrrev_i32_e32 v12, 10, v1
	v_mul_i32_i24_e32 v1, 0x400, v12
	v_sub_u32_e32 v0, v0, v1
	v_lshrrev_b32_e32 v1, 4, v0
	v_bitop3_b32 v0, v1, v0, 32 bitop3:0x6c
	v_lshl_add_u32 v128, v2, 13, v4
	v_ashrrev_i32_e32 v2, 31, v0
	s_add_u32 s33, s94, 0x1c100000
	v_lshrrev_b32_e32 v2, 26, v2
	s_addc_u32 s54, s95, 0
	v_add_u32_e32 v2, v0, v2
	s_add_i32 s0, s4, s0
	v_lshlrev_b32_e32 v1, 3, v12
	v_ashrrev_i32_e32 v13, 6, v2
	v_and_b32_e32 v2, 0xc0, v2
	s_ashr_i32 s4, s0, 31
	v_and_b32_e32 v1, -16, v1
	v_sub_u32_e32 v0, v0, v2
	s_lshr_b32 s4, s4, 25
	v_add_u32_e32 v1, v13, v1
	v_ashrrev_i16_sdwa v0, v3, sext(v0) dst_sel:DWORD dst_unused:UNUSED_PAD src0_sel:DWORD src1_sel:BYTE_0
	v_and_b32_e32 v3, 3, v13
	s_add_i32 s4, s0, s4
	v_and_or_b32 v3, v1, s5, v3
	s_ashr_i32 s5, s4, 7
	s_and_b32 s4, s4, 0xffffff80
	s_sub_i32 s4, s0, s4
	s_bfe_i32 s0, s4, 0x80000
	s_bfe_u32 s0, s0, 0x3000c
	s_add_i32 s6, s4, s0
	s_bfe_i32 s0, s6, 0x80000
	s_and_b32 s6, s6, 0xf8
	s_sub_i32 s4, s4, s6
	s_lshl_b32 s5, s5, 3
	s_sext_i32_i16 s0, s0
	s_sext_i32_i8 s4, s4
	s_ashr_i32 s1, s10, 6
	s_lshr_b32 s0, s0, 3
	s_add_i32 s18, s5, s4
	s_ashr_i32 s19, s18, 31
	s_bfe_i64 s[6:7], s[0:1], 0x100000
	s_ashr_i32 s11, s10, 8
	s_lshl_b32 s55, s1, 10
	s_lshl_b64 s[4:5], s[18:19], 21
	s_lshl_b64 s[6:7], s[6:7], 21
	s_add_u32 s50, s92, s6
	v_readlane_b32 s6, v254, 42
	v_lshlrev_b32_e32 v4, 5, v12
	v_bfe_i32 v14, v0, 0, 16
	v_lshlrev_b32_e32 v0, 1, v1
	v_lshrrev_b32_e32 v2, 2, v1
	s_addc_u32 s51, s6, s7
	s_add_i32 s19, s55, 0
	v_and_b32_e32 v4, 32, v4
	v_and_b32_e32 v0, 24, v0
	v_and_b32_e32 v2, 4, v2
	s_add_i32 m0, s19, 0x10000
	v_or3_b32 v0, v3, v2, v0
	v_add_lshl_u32 v2, v4, v14, 1
	global_load_lds_dwordx4 v130, s[50:51]
	s_add_i32 m0, s19, 0x12000
	v_lshl_add_u32 v134, v0, 13, v2
	v_add_u32_e32 v134, s101, v134
	v_add_u32_e32 v134, 0x80000, v134
	s_add_u32 s6, s50, 0x40000
	global_load_lds_dwordx4 v134, s[50:51]
	s_addc_u32 s7, s51, 0
	s_add_i32 m0, s19, 0x14000
	v_lshl_add_u32 v132, v1, 13, v2
	global_load_lds_dwordx4 v130, s[6:7]
	s_add_i32 m0, s19, 0x16000
	s_add_u32 s48, s33, s4
	s_addc_u32 s49, s54, s5
	s_add_i32 s56, s19, 0x2000
	global_load_lds_dwordx4 v134, s[6:7]
	s_mov_b32 m0, s19
	s_add_u32 s4, s48, 0x100000
	global_load_lds_dwordx4 v128, s[48:49]
	s_mov_b32 m0, s56
	s_addc_u32 s5, s49, 0
	s_add_i32 s57, s19, 0x4000
	global_load_lds_dwordx4 v132, s[48:49]
	s_mov_b32 m0, s57
	s_add_i32 s58, s19, 0x6000
	global_load_lds_dwordx4 v128, s[4:5]
	s_mov_b32 m0, s58
	v_mov_b32_e32 v131, 0
	global_load_lds_dwordx4 v132, s[4:5]
	v_mov_b32_e32 v135, v131
	v_mov_b32_e32 v129, v131
	v_mov_b32_e32 v133, v131
	s_cmp_eq_u32 s11, 1
	s_mov_b32 s59, 0
	v_lshl_add_u64 v[6:7], s[50:51], 0, v[130:131]
	v_lshl_add_u64 v[2:3], s[50:51], 0, v[134:135]
	v_lshl_add_u64 v[0:1], s[48:49], 0, v[128:129]
	s_cselect_b64 s[4:5], -1, 0
	s_cmp_lg_u32 s11, 1
	v_lshl_add_u64 v[4:5], s[48:49], 0, v[132:133]
	s_cbranch_scc1 .LBB0_590
	s_barrier
.LBB0_590:
	s_add_u32 s6, s94, 0x2c100000
	s_addc_u32 s7, s95, 0
	s_lshl_b32 s1, s1, 5
	s_mov_b64 s[8:9], 0x80
	s_and_b32 s1, s1, 0x60
	s_add_i32 m0, s19, 0x18000
	v_lshl_add_u64 v[6:7], v[6:7], 0, s[8:9]
	s_lshl_b32 s16, s11, 13
	s_lshl_b32 s17, s1, 7
	s_waitcnt vmcnt(2)
	s_barrier
	global_load_lds_dwordx4 v[6:7], off
	v_lshl_add_u64 v[2:3], v[2:3], 0, s[8:9]
	s_add_i32 m0, s19, 0x1a000
	s_add_i32 s60, s19, 0x8000
	s_add_i32 s61, s19, 0xa000
	global_load_lds_dwordx4 v[2:3], off
	v_lshl_add_u64 v[0:1], v[0:1], 0, s[8:9]
	s_mov_b32 m0, s60
	s_add_u32 s12, s50, 0x40080
	global_load_lds_dwordx4 v[0:1], off
	v_lshl_add_u64 v[0:1], v[4:5], 0, s[8:9]
	s_mov_b32 m0, s61
	s_addc_u32 s13, s51, 0
	global_load_lds_dwordx4 v[0:1], off
	s_add_i32 m0, s19, 0x1c000
	v_lshl_add_u64 v[0:1], s[12:13], 0, v[130:131]
	global_load_lds_dwordx4 v[0:1], off
	v_lshl_add_u64 v[0:1], s[12:13], 0, v[134:135]
	s_add_i32 m0, s19, 0x1e000
	s_cmpk_lt_u32 s10, 0x100
	global_load_lds_dwordx4 v[0:1], off
	v_lshrrev_b32_e32 v1, 1, v9
	v_and_b32_e32 v1, 24, v1
	v_and_b32_e32 v0, 15, v9
	v_lshlrev_b32_e32 v2, 1, v1
	v_lshl_or_b32 v146, s11, 6, v0
	v_lshl_or_b32 v0, v0, 6, v2
	v_lshlrev_b32_e32 v2, 2, v9
	v_and_b32_e32 v2, 32, v2
	v_bitop3_b32 v3, v0, s16, v2 bitop3:0xde
	v_bitop3_b32 v147, s17, v0, v2 bitop3:0xf6
	v_lshlrev_b32_e32 v0, 16, v8
	v_and_b32_e32 v0, 0xfffe0000, v0
	v_or_b32_e32 v148, s1, v1
	v_lshl_add_u32 v0, v10, 13, v0
	v_and_b32_e32 v1, 1, v8
	v_lshl_or_b32 v0, v1, 6, v0
	v_lshl_add_u32 v136, v11, 1, v0
	v_lshlrev_b32_e32 v0, 16, v12
	v_and_b32_e32 v0, 0xfffe0000, v0
	s_waitcnt vmcnt(6)
	v_lshl_add_u32 v0, v13, 13, v0
	v_and_b32_e32 v1, 1, v12
	s_cselect_b64 s[10:11], -1, 0
	v_lshl_or_b32 v0, v1, 6, v0
	s_add_i32 s63, 0, 0x10000
	s_add_i32 s64, 0, 0x14000
	s_sext_i32_i8 s65, s0
	s_ashr_i32 s62, s15, 31
	v_mov_b32_e32 v137, v131
	v_lshl_add_u32 v138, v14, 1, v0
	v_mov_b32_e32 v139, v131
	v_mov_b64_e32 v[140:141], 0x800
	v_mov_b64_e32 v[142:143], 0x7ff
	v_add_u32_e32 v149, s63, v147
	v_add_u32_e32 v150, s64, v147
	v_add_u32_e32 v151, 0, v3
	s_barrier
	s_waitcnt vmcnt(0)
	s_branch .LBB0_593

.Lmy_prio_skip2:
.LBB0_600:
	ds_read_b128 v[152:155], v149
	ds_read_b128 v[156:159], v149 offset:1024
	ds_read_b128 v[160:163], v149 offset:2048
	ds_read_b128 v[164:167], v149 offset:3072
	ds_read_b128 v[168:171], v150
	ds_read_b128 v[172:175], v150 offset:1024
	ds_read_b128 v[176:179], v150 offset:2048
	ds_read_b128 v[180:183], v150 offset:3072
	s_add_u32 s37, s48, 0xfff00080
	s_addc_u32 s38, s49, -1
	s_cmp_eq_u32 s36, 60
	s_cselect_b32 s53, s17, s38
	s_cselect_b32 s52, s66, s37
	s_cselect_b32 s51, s13, s35
	s_cselect_b32 s50, s67, s34
	s_add_i32 m0, s19, 0xc000
	ds_read_b128 v[184:187], v151
	ds_read_b128 v[188:191], v151 offset:1024
	ds_read_b128 v[192:195], v151 offset:2048
	ds_read_b128 v[196:199], v151 offset:3072
	ds_read_b128 v[200:203], v151 offset:4096
	ds_read_b128 v[204:207], v151 offset:5120
	ds_read_b128 v[208:211], v151 offset:6144
	ds_read_b128 v[212:215], v151 offset:7168
	global_load_lds_dwordx4 v136, s[48:49]
	s_add_i32 m0, s19, 0xe000
	s_nop 0
	global_load_lds_dwordx4 v138, s[48:49]
	s_waitcnt vmcnt(8)
	s_waitcnt lgkmcnt(0)
	s_barrier
	s_waitcnt lgkmcnt(0)
	v_mfma_f32_16x16x32_bf16 v[124:127], v[152:155], v[184:187], v[124:127]
	v_mfma_f32_16x16x32_bf16 v[120:123], v[160:163], v[184:187], v[120:123]
	v_mfma_f32_16x16x32_bf16 v[116:119], v[152:155], v[192:195], v[116:119]
	v_mfma_f32_16x16x32_bf16 v[108:111], v[160:163], v[192:195], v[108:111]
	v_mfma_f32_16x16x32_bf16 v[100:103], v[152:155], v[200:203], v[100:103]
	v_mfma_f32_16x16x32_bf16 v[92:95], v[160:163], v[200:203], v[92:95]
	v_mfma_f32_16x16x32_bf16 v[84:87], v[152:155], v[208:211], v[84:87]
	v_mfma_f32_16x16x32_bf16 v[76:79], v[160:163], v[208:211], v[76:79]
	v_mfma_f32_16x16x32_bf16 v[124:127], v[156:159], v[188:191], v[124:127]
	v_mfma_f32_16x16x32_bf16 v[120:123], v[164:167], v[188:191], v[120:123]
	v_mfma_f32_16x16x32_bf16 v[116:119], v[156:159], v[196:199], v[116:119]
	v_mfma_f32_16x16x32_bf16 v[108:111], v[164:167], v[196:199], v[108:111]
	v_mfma_f32_16x16x32_bf16 v[100:103], v[156:159], v[204:207], v[100:103]
	v_mfma_f32_16x16x32_bf16 v[92:95], v[164:167], v[204:207], v[92:95]
	v_mfma_f32_16x16x32_bf16 v[84:87], v[156:159], v[212:215], v[84:87]
	v_mfma_f32_16x16x32_bf16 v[76:79], v[164:167], v[212:215], v[76:79]
	v_mfma_f32_16x16x32_bf16 v[112:115], v[168:171], v[184:187], v[112:115]
	v_mfma_f32_16x16x32_bf16 v[104:107], v[176:179], v[184:187], v[104:107]
	v_mfma_f32_16x16x32_bf16 v[96:99], v[168:171], v[192:195], v[96:99]
	v_mfma_f32_16x16x32_bf16 v[88:91], v[176:179], v[192:195], v[88:91]
	v_mfma_f32_16x16x32_bf16 v[80:83], v[168:171], v[200:203], v[80:83]
	v_mfma_f32_16x16x32_bf16 v[72:75], v[176:179], v[200:203], v[72:75]
	v_mfma_f32_16x16x32_bf16 v[68:71], v[168:171], v[208:211], v[68:71]
	v_mfma_f32_16x16x32_bf16 v[64:67], v[176:179], v[208:211], v[64:67]
	v_mfma_f32_16x16x32_bf16 v[112:115], v[172:175], v[188:191], v[112:115]
	v_mfma_f32_16x16x32_bf16 v[104:107], v[180:183], v[188:191], v[104:107]
	v_mfma_f32_16x16x32_bf16 v[96:99], v[172:175], v[196:199], v[96:99]
	v_mfma_f32_16x16x32_bf16 v[88:91], v[180:183], v[196:199], v[88:91]
	v_mfma_f32_16x16x32_bf16 v[80:83], v[172:175], v[204:207], v[80:83]
	v_mfma_f32_16x16x32_bf16 v[72:75], v[180:183], v[204:207], v[72:75]
	v_mfma_f32_16x16x32_bf16 v[68:71], v[172:175], v[212:215], v[68:71]
	v_mfma_f32_16x16x32_bf16 v[64:67], v[180:183], v[212:215], v[64:67]
	s_barrier
	s_add_i32 s37, s63, s55
	s_mov_b32 m0, s37
	ds_read_b128 v[184:187], v151 offset:16384
	ds_read_b128 v[188:191], v151 offset:17408
	ds_read_b128 v[192:195], v151 offset:18432
	ds_read_b128 v[196:199], v151 offset:19456
	ds_read_b128 v[200:203], v151 offset:20480
	ds_read_b128 v[204:207], v151 offset:21504
	ds_read_b128 v[208:211], v151 offset:22528
	ds_read_b128 v[212:215], v151 offset:23552
	global_load_lds_dwordx4 v130, s[50:51]
	s_add_i32 m0, s37, 0x2000
	s_add_u32 s38, s50, 0x40000
	s_addc_u32 s39, s51, 0
	s_add_i32 s37, s64, s55
	global_load_lds_dwordx4 v134, s[50:51]
	s_mov_b32 m0, s37
	global_load_lds_dwordx4 v130, s[38:39]
	s_add_i32 m0, s37, 0x2000
	s_nop 0
	global_load_lds_dwordx4 v134, s[38:39]
	s_mov_b32 m0, s19
	s_nop 0
	global_load_lds_dwordx4 v128, s[52:53]
	s_mov_b32 m0, s56
	s_nop 0
	global_load_lds_dwordx4 v132, s[52:53]
	s_waitcnt vmcnt(8)
	s_waitcnt lgkmcnt(0)
	s_barrier
	s_waitcnt lgkmcnt(0)
	v_mfma_f32_16x16x32_bf16 v[60:63], v[152:155], v[184:187], v[60:63]
	v_mfma_f32_16x16x32_bf16 v[56:59], v[160:163], v[184:187], v[56:59]
	v_mfma_f32_16x16x32_bf16 v[52:55], v[152:155], v[192:195], v[52:55]
	v_mfma_f32_16x16x32_bf16 v[44:47], v[160:163], v[192:195], v[44:47]
	v_mfma_f32_16x16x32_bf16 v[36:39], v[152:155], v[200:203], v[36:39]
	v_mfma_f32_16x16x32_bf16 v[28:31], v[160:163], v[200:203], v[28:31]
	v_mfma_f32_16x16x32_bf16 v[20:23], v[152:155], v[208:211], v[20:23]
	v_mfma_f32_16x16x32_bf16 v[12:15], v[160:163], v[208:211], v[12:15]
	v_mfma_f32_16x16x32_bf16 v[60:63], v[156:159], v[188:191], v[60:63]
	v_mfma_f32_16x16x32_bf16 v[56:59], v[164:167], v[188:191], v[56:59]
	v_mfma_f32_16x16x32_bf16 v[52:55], v[156:159], v[196:199], v[52:55]
	v_mfma_f32_16x16x32_bf16 v[44:47], v[164:167], v[196:199], v[44:47]
	v_mfma_f32_16x16x32_bf16 v[36:39], v[156:159], v[204:207], v[36:39]
	v_mfma_f32_16x16x32_bf16 v[28:31], v[164:167], v[204:207], v[28:31]
	v_mfma_f32_16x16x32_bf16 v[20:23], v[156:159], v[212:215], v[20:23]
	v_mfma_f32_16x16x32_bf16 v[12:15], v[164:167], v[212:215], v[12:15]
	v_mfma_f32_16x16x32_bf16 v[48:51], v[168:171], v[184:187], v[48:51]
	v_mfma_f32_16x16x32_bf16 v[40:43], v[176:179], v[184:187], v[40:43]
	v_mfma_f32_16x16x32_bf16 v[32:35], v[168:171], v[192:195], v[32:35]
	v_mfma_f32_16x16x32_bf16 v[24:27], v[176:179], v[192:195], v[24:27]
	v_mfma_f32_16x16x32_bf16 v[16:19], v[168:171], v[200:203], v[16:19]
	v_mfma_f32_16x16x32_bf16 v[8:11], v[176:179], v[200:203], v[8:11]
	v_mfma_f32_16x16x32_bf16 v[4:7], v[168:171], v[208:211], v[4:7]
	v_mfma_f32_16x16x32_bf16 v[0:3], v[176:179], v[208:211], v[0:3]
	v_mfma_f32_16x16x32_bf16 v[48:51], v[172:175], v[188:191], v[48:51]
	v_mfma_f32_16x16x32_bf16 v[40:43], v[180:183], v[188:191], v[40:43]
	v_mfma_f32_16x16x32_bf16 v[32:35], v[172:175], v[196:199], v[32:35]
	v_mfma_f32_16x16x32_bf16 v[24:27], v[180:183], v[196:199], v[24:27]
	v_mfma_f32_16x16x32_bf16 v[16:19], v[172:175], v[204:207], v[16:19]
	v_mfma_f32_16x16x32_bf16 v[8:11], v[180:183], v[204:207], v[8:11]
	v_mfma_f32_16x16x32_bf16 v[4:7], v[172:175], v[212:215], v[4:7]
	v_mfma_f32_16x16x32_bf16 v[0:3], v[180:183], v[212:215], v[0:3]
	s_barrier
	s_add_i32 s37, 0, 0x18000
	s_add_i32 s40, 0, 0x1c000
	v_add_u32_e32 v164, s37, v147
	v_add_u32_e32 v180, s40, v147
	ds_read_b128 v[152:155], v164
	ds_read_b128 v[156:159], v164 offset:1024
	ds_read_b128 v[160:163], v164 offset:2048
	ds_read_b128 v[164:167], v164 offset:3072
	ds_read_b128 v[168:171], v180
	ds_read_b128 v[172:175], v180 offset:1024
	ds_read_b128 v[176:179], v180 offset:2048
	ds_read_b128 v[180:183], v180 offset:3072
	s_add_u32 s38, s52, 0x100000
	s_addc_u32 s39, s53, 0
	s_mov_b32 m0, s57
	ds_read_b128 v[184:187], v151 offset:32768
	ds_read_b128 v[188:191], v151 offset:33792
	ds_read_b128 v[192:195], v151 offset:34816
	ds_read_b128 v[196:199], v151 offset:35840
	ds_read_b128 v[200:203], v151 offset:36864
	ds_read_b128 v[204:207], v151 offset:37888
	ds_read_b128 v[208:211], v151 offset:38912
	ds_read_b128 v[212:215], v151 offset:39936
	global_load_lds_dwordx4 v128, s[38:39]
	s_mov_b32 m0, s58
	s_nop 0
	global_load_lds_dwordx4 v132, s[38:39]
	s_waitcnt vmcnt(8)
	s_waitcnt lgkmcnt(0)
	s_barrier
	s_waitcnt lgkmcnt(0)
	v_mfma_f32_16x16x32_bf16 v[124:127], v[152:155], v[184:187], v[124:127]
	v_mfma_f32_16x16x32_bf16 v[120:123], v[160:163], v[184:187], v[120:123]
	v_mfma_f32_16x16x32_bf16 v[116:119], v[152:155], v[192:195], v[116:119]
	v_mfma_f32_16x16x32_bf16 v[108:111], v[160:163], v[192:195], v[108:111]
	v_mfma_f32_16x16x32_bf16 v[100:103], v[152:155], v[200:203], v[100:103]
	v_mfma_f32_16x16x32_bf16 v[92:95], v[160:163], v[200:203], v[92:95]
	v_mfma_f32_16x16x32_bf16 v[84:87], v[152:155], v[208:211], v[84:87]
	v_mfma_f32_16x16x32_bf16 v[76:79], v[160:163], v[208:211], v[76:79]
	v_mfma_f32_16x16x32_bf16 v[124:127], v[156:159], v[188:191], v[124:127]
	v_mfma_f32_16x16x32_bf16 v[120:123], v[164:167], v[188:191], v[120:123]
	v_mfma_f32_16x16x32_bf16 v[116:119], v[156:159], v[196:199], v[116:119]
	v_mfma_f32_16x16x32_bf16 v[108:111], v[164:167], v[196:199], v[108:111]
	v_mfma_f32_16x16x32_bf16 v[100:103], v[156:159], v[204:207], v[100:103]
	v_mfma_f32_16x16x32_bf16 v[92:95], v[164:167], v[204:207], v[92:95]
	v_mfma_f32_16x16x32_bf16 v[84:87], v[156:159], v[212:215], v[84:87]
	v_mfma_f32_16x16x32_bf16 v[76:79], v[164:167], v[212:215], v[76:79]
	v_mfma_f32_16x16x32_bf16 v[112:115], v[168:171], v[184:187], v[112:115]
	v_mfma_f32_16x16x32_bf16 v[104:107], v[176:179], v[184:187], v[104:107]
	v_mfma_f32_16x16x32_bf16 v[96:99], v[168:171], v[192:195], v[96:99]
	v_mfma_f32_16x16x32_bf16 v[88:91], v[176:179], v[192:195], v[88:91]
	v_mfma_f32_16x16x32_bf16 v[80:83], v[168:171], v[200:203], v[80:83]
	v_mfma_f32_16x16x32_bf16 v[72:75], v[176:179], v[200:203], v[72:75]
	v_mfma_f32_16x16x32_bf16 v[68:71], v[168:171], v[208:211], v[68:71]
	v_mfma_f32_16x16x32_bf16 v[64:67], v[176:179], v[208:211], v[64:67]
	v_mfma_f32_16x16x32_bf16 v[112:115], v[172:175], v[188:191], v[112:115]
	v_mfma_f32_16x16x32_bf16 v[104:107], v[180:183], v[188:191], v[104:107]
	v_mfma_f32_16x16x32_bf16 v[96:99], v[172:175], v[196:199], v[96:99]
	v_mfma_f32_16x16x32_bf16 v[88:91], v[180:183], v[196:199], v[88:91]
	v_mfma_f32_16x16x32_bf16 v[80:83], v[172:175], v[204:207], v[80:83]
	v_mfma_f32_16x16x32_bf16 v[72:75], v[180:183], v[204:207], v[72:75]
	v_mfma_f32_16x16x32_bf16 v[68:71], v[172:175], v[212:215], v[68:71]
	v_mfma_f32_16x16x32_bf16 v[64:67], v[180:183], v[212:215], v[64:67]
	s_barrier
	s_add_i32 s37, s37, s55
	s_mov_b32 m0, s37
	ds_read_b128 v[184:187], v151 offset:49152
	ds_read_b128 v[188:191], v151 offset:50176
	ds_read_b128 v[192:195], v151 offset:51200
	ds_read_b128 v[196:199], v151 offset:52224
	ds_read_b128 v[200:203], v151 offset:53248
	ds_read_b128 v[204:207], v151 offset:54272
	ds_read_b128 v[208:211], v151 offset:55296
	ds_read_b128 v[212:215], v151 offset:56320
	s_add_u32 s100, s50, 0x80
	s_addc_u32 s101, s51, 0
	global_load_lds_dwordx4 v130, s[100:101]
	s_add_i32 m0, s37, 0x2000
	s_add_u32 s38, s50, 0x40080
	s_addc_u32 s39, s51, 0
	s_add_i32 s37, s40, s55
	s_add_u32 s100, s50, 0x80
	s_addc_u32 s101, s51, 0
	global_load_lds_dwordx4 v134, s[100:101]
	s_mov_b32 m0, s37
	s_nop 0
	global_load_lds_dwordx4 v130, s[38:39]
	s_add_i32 m0, s37, 0x2000
	s_nop 0
	global_load_lds_dwordx4 v134, s[38:39]
	s_mov_b32 m0, s60
	s_nop 0
	s_add_u32 s100, s52, 0x80
	s_addc_u32 s101, s53, 0
	global_load_lds_dwordx4 v128, s[100:101]
	s_mov_b32 m0, s61
	s_nop 0
	s_add_u32 s100, s52, 0x80
	s_addc_u32 s101, s53, 0
	global_load_lds_dwordx4 v132, s[100:101]
	s_waitcnt vmcnt(8)
	s_waitcnt lgkmcnt(0)
	s_barrier
	s_waitcnt lgkmcnt(0)
	v_mfma_f32_16x16x32_bf16 v[60:63], v[152:155], v[184:187], v[60:63]
	v_mfma_f32_16x16x32_bf16 v[56:59], v[160:163], v[184:187], v[56:59]
	v_mfma_f32_16x16x32_bf16 v[52:55], v[152:155], v[192:195], v[52:55]
	v_mfma_f32_16x16x32_bf16 v[44:47], v[160:163], v[192:195], v[44:47]
	v_mfma_f32_16x16x32_bf16 v[36:39], v[152:155], v[200:203], v[36:39]
	v_mfma_f32_16x16x32_bf16 v[28:31], v[160:163], v[200:203], v[28:31]
	v_mfma_f32_16x16x32_bf16 v[20:23], v[152:155], v[208:211], v[20:23]
	v_mfma_f32_16x16x32_bf16 v[12:15], v[160:163], v[208:211], v[12:15]
	v_mfma_f32_16x16x32_bf16 v[60:63], v[156:159], v[188:191], v[60:63]
	v_mfma_f32_16x16x32_bf16 v[56:59], v[164:167], v[188:191], v[56:59]
	v_mfma_f32_16x16x32_bf16 v[52:55], v[156:159], v[196:199], v[52:55]
	v_mfma_f32_16x16x32_bf16 v[44:47], v[164:167], v[196:199], v[44:47]
	v_mfma_f32_16x16x32_bf16 v[36:39], v[156:159], v[204:207], v[36:39]
	v_mfma_f32_16x16x32_bf16 v[28:31], v[164:167], v[204:207], v[28:31]
	v_mfma_f32_16x16x32_bf16 v[20:23], v[156:159], v[212:215], v[20:23]
	v_mfma_f32_16x16x32_bf16 v[12:15], v[164:167], v[212:215], v[12:15]
	v_mfma_f32_16x16x32_bf16 v[48:51], v[168:171], v[184:187], v[48:51]
	v_mfma_f32_16x16x32_bf16 v[40:43], v[176:179], v[184:187], v[40:43]
	v_mfma_f32_16x16x32_bf16 v[32:35], v[168:171], v[192:195], v[32:35]
	v_mfma_f32_16x16x32_bf16 v[24:27], v[176:179], v[192:195], v[24:27]
	v_mfma_f32_16x16x32_bf16 v[16:19], v[168:171], v[200:203], v[16:19]
	v_mfma_f32_16x16x32_bf16 v[8:11], v[176:179], v[200:203], v[8:11]
	v_mfma_f32_16x16x32_bf16 v[4:7], v[168:171], v[208:211], v[4:7]
	v_mfma_f32_16x16x32_bf16 v[0:3], v[176:179], v[208:211], v[0:3]
	v_mfma_f32_16x16x32_bf16 v[48:51], v[172:175], v[188:191], v[48:51]
	v_mfma_f32_16x16x32_bf16 v[40:43], v[180:183], v[188:191], v[40:43]
	v_mfma_f32_16x16x32_bf16 v[32:35], v[172:175], v[196:199], v[32:35]
	v_mfma_f32_16x16x32_bf16 v[24:27], v[180:183], v[196:199], v[24:27]
	v_mfma_f32_16x16x32_bf16 v[16:19], v[172:175], v[204:207], v[16:19]
	v_mfma_f32_16x16x32_bf16 v[8:11], v[180:183], v[204:207], v[8:11]
	v_mfma_f32_16x16x32_bf16 v[4:7], v[172:175], v[212:215], v[4:7]
	v_mfma_f32_16x16x32_bf16 v[0:3], v[180:183], v[212:215], v[0:3]
	s_barrier
	s_add_i32 s36, s36, 2
	s_add_u32 s48, s48, 0x100
	s_addc_u32 s49, s49, 0
	s_add_u32 s34, s34, 0x100
	s_addc_u32 s35, s35, 0
	s_cmp_gt_u32 s36, 61
	s_cbranch_scc0 .LBB0_600
	s_setprio 0
	s_and_b64 vcc, exec, s[10:11]
	s_cbranch_vccz .LBB0_603
	s_barrier
.LBB0_603:
	v_and_b32_e32 v152, 0xfffffff7, v146
	v_lshl_add_u32 v152, s18, 8, v152
	v_and_b32_e32 v153, 0x60, v148
	v_add_u32_e32 v153, v153, v148
	v_lshl_or_b32 v153, s65, 8, v153
	v_bfe_u32 v154, v146, 3, 1
	v_lshlrev_b32_e32 v152, 13, v152
	v_lshl_add_u32 v152, v153, 1, v152
	v_lshl_add_u32 v152, v154, 6, v152
	v_cvt_pk_bf16_f32 v124, v124, v125
	v_cvt_pk_bf16_f32 v125, v126, v127
	v_cvt_pk_bf16_f32 v126, v120, v121
	v_cvt_pk_bf16_f32 v127, v122, v123
	v_cvt_pk_bf16_f32 v112, v112, v113
	v_cvt_pk_bf16_f32 v113, v114, v115
	v_cvt_pk_bf16_f32 v114, v104, v105
	v_cvt_pk_bf16_f32 v115, v106, v107
	s_add_u32 s100, s6, 0x0
	s_addc_u32 s101, s7, 0
	v_mov_b32_dpp v120, v124 row_ror:8 row_mask:0xf bank_mask:0xf
	v_mov_b32_dpp v121, v125 row_ror:8 row_mask:0xf bank_mask:0xf
	v_mov_b32_dpp v122, v126 row_ror:8 row_mask:0xf bank_mask:0xf
	v_mov_b32_dpp v123, v127 row_ror:8 row_mask:0xf bank_mask:0xf
	v_mov_b32_dpp v124, v112 row_ror:8 row_mask:0xf bank_mask:0xc
	v_mov_b32_dpp v125, v113 row_ror:8 row_mask:0xf bank_mask:0xc
	v_mov_b32_dpp v126, v114 row_ror:8 row_mask:0xf bank_mask:0xc
	v_mov_b32_dpp v127, v115 row_ror:8 row_mask:0xf bank_mask:0xc
	v_mov_b32_dpp v112, v120 quad_perm:[0,1,2,3] row_mask:0xf bank_mask:0x3
	v_mov_b32_dpp v113, v121 quad_perm:[0,1,2,3] row_mask:0xf bank_mask:0x3
	v_mov_b32_dpp v114, v122 quad_perm:[0,1,2,3] row_mask:0xf bank_mask:0x3
	v_mov_b32_dpp v115, v123 quad_perm:[0,1,2,3] row_mask:0xf bank_mask:0x3
	global_store_dwordx4 v152, v[124:127], s[100:101]
	s_add_u32 s100, s100, 0x10000
	s_addc_u32 s101, s101, 0
	global_store_dwordx4 v152, v[112:115], s[100:101]
	v_cvt_pk_bf16_f32 v116, v116, v117
	v_cvt_pk_bf16_f32 v117, v118, v119
	v_cvt_pk_bf16_f32 v118, v108, v109
	v_cvt_pk_bf16_f32 v119, v110, v111
	v_cvt_pk_bf16_f32 v96, v96, v97
	v_cvt_pk_bf16_f32 v97, v98, v99
	v_cvt_pk_bf16_f32 v98, v88, v89
	v_cvt_pk_bf16_f32 v99, v90, v91
	s_add_u32 s100, s6, 0x20000
	s_addc_u32 s101, s7, 0
	v_mov_b32_dpp v108, v116 row_ror:8 row_mask:0xf bank_mask:0xf
	v_mov_b32_dpp v109, v117 row_ror:8 row_mask:0xf bank_mask:0xf
	v_mov_b32_dpp v110, v118 row_ror:8 row_mask:0xf bank_mask:0xf
	v_mov_b32_dpp v111, v119 row_ror:8 row_mask:0xf bank_mask:0xf
	v_mov_b32_dpp v116, v96 row_ror:8 row_mask:0xf bank_mask:0xc
	v_mov_b32_dpp v117, v97 row_ror:8 row_mask:0xf bank_mask:0xc
	v_mov_b32_dpp v118, v98 row_ror:8 row_mask:0xf bank_mask:0xc
	v_mov_b32_dpp v119, v99 row_ror:8 row_mask:0xf bank_mask:0xc
	v_mov_b32_dpp v96, v108 quad_perm:[0,1,2,3] row_mask:0xf bank_mask:0x3
	v_mov_b32_dpp v97, v109 quad_perm:[0,1,2,3] row_mask:0xf bank_mask:0x3
	v_mov_b32_dpp v98, v110 quad_perm:[0,1,2,3] row_mask:0xf bank_mask:0x3
	v_mov_b32_dpp v99, v111 quad_perm:[0,1,2,3] row_mask:0xf bank_mask:0x3
	global_store_dwordx4 v152, v[116:119], s[100:101]
	s_add_u32 s100, s100, 0x10000
	s_addc_u32 s101, s101, 0
	global_store_dwordx4 v152, v[96:99], s[100:101]
	v_cvt_pk_bf16_f32 v100, v100, v101
	v_cvt_pk_bf16_f32 v101, v102, v103
	v_cvt_pk_bf16_f32 v102, v92, v93
	v_cvt_pk_bf16_f32 v103, v94, v95
	v_cvt_pk_bf16_f32 v80, v80, v81
	v_cvt_pk_bf16_f32 v81, v82, v83
	v_cvt_pk_bf16_f32 v82, v72, v73
	v_cvt_pk_bf16_f32 v83, v74, v75
	s_add_u32 s100, s6, 0x40000
	s_addc_u32 s101, s7, 0
	v_mov_b32_dpp v92, v100 row_ror:8 row_mask:0xf bank_mask:0xf
	v_mov_b32_dpp v93, v101 row_ror:8 row_mask:0xf bank_mask:0xf
	v_mov_b32_dpp v94, v102 row_ror:8 row_mask:0xf bank_mask:0xf
	v_mov_b32_dpp v95, v103 row_ror:8 row_mask:0xf bank_mask:0xf
	v_mov_b32_dpp v100, v80 row_ror:8 row_mask:0xf bank_mask:0xc
	v_mov_b32_dpp v101, v81 row_ror:8 row_mask:0xf bank_mask:0xc
	v_mov_b32_dpp v102, v82 row_ror:8 row_mask:0xf bank_mask:0xc
	v_mov_b32_dpp v103, v83 row_ror:8 row_mask:0xf bank_mask:0xc
	v_mov_b32_dpp v80, v92 quad_perm:[0,1,2,3] row_mask:0xf bank_mask:0x3
	v_mov_b32_dpp v81, v93 quad_perm:[0,1,2,3] row_mask:0xf bank_mask:0x3
	v_mov_b32_dpp v82, v94 quad_perm:[0,1,2,3] row_mask:0xf bank_mask:0x3
	v_mov_b32_dpp v83, v95 quad_perm:[0,1,2,3] row_mask:0xf bank_mask:0x3
	global_store_dwordx4 v152, v[100:103], s[100:101]
	s_add_u32 s100, s100, 0x10000
	s_addc_u32 s101, s101, 0
	global_store_dwordx4 v152, v[80:83], s[100:101]
	v_cvt_pk_bf16_f32 v84, v84, v85
	v_cvt_pk_bf16_f32 v85, v86, v87
	v_cvt_pk_bf16_f32 v86, v76, v77
	v_cvt_pk_bf16_f32 v87, v78, v79
	v_cvt_pk_bf16_f32 v68, v68, v69
	v_cvt_pk_bf16_f32 v69, v70, v71
	v_cvt_pk_bf16_f32 v70, v64, v65
	v_cvt_pk_bf16_f32 v71, v66, v67
	s_add_u32 s100, s6, 0x60000
	s_addc_u32 s101, s7, 0
	v_mov_b32_dpp v76, v84 row_ror:8 row_mask:0xf bank_mask:0xf
	v_mov_b32_dpp v77, v85 row_ror:8 row_mask:0xf bank_mask:0xf
	v_mov_b32_dpp v78, v86 row_ror:8 row_mask:0xf bank_mask:0xf
	v_mov_b32_dpp v79, v87 row_ror:8 row_mask:0xf bank_mask:0xf
	v_mov_b32_dpp v84, v68 row_ror:8 row_mask:0xf bank_mask:0xc
	v_mov_b32_dpp v85, v69 row_ror:8 row_mask:0xf bank_mask:0xc
	v_mov_b32_dpp v86, v70 row_ror:8 row_mask:0xf bank_mask:0xc
	v_mov_b32_dpp v87, v71 row_ror:8 row_mask:0xf bank_mask:0xc
	v_mov_b32_dpp v68, v76 quad_perm:[0,1,2,3] row_mask:0xf bank_mask:0x3
	v_mov_b32_dpp v69, v77 quad_perm:[0,1,2,3] row_mask:0xf bank_mask:0x3
	v_mov_b32_dpp v70, v78 quad_perm:[0,1,2,3] row_mask:0xf bank_mask:0x3
	v_mov_b32_dpp v71, v79 quad_perm:[0,1,2,3] row_mask:0xf bank_mask:0x3
	global_store_dwordx4 v152, v[84:87], s[100:101]
	s_add_u32 s100, s100, 0x10000
	s_addc_u32 s101, s101, 0
	global_store_dwordx4 v152, v[68:71], s[100:101]
	v_cvt_pk_bf16_f32 v60, v60, v61
	v_cvt_pk_bf16_f32 v61, v62, v63
	v_cvt_pk_bf16_f32 v62, v56, v57
	v_cvt_pk_bf16_f32 v63, v58, v59
	v_cvt_pk_bf16_f32 v48, v48, v49
	v_cvt_pk_bf16_f32 v49, v50, v51
	v_cvt_pk_bf16_f32 v50, v40, v41
	v_cvt_pk_bf16_f32 v51, v42, v43
	s_add_u32 s100, s6, 0x100000
	s_addc_u32 s101, s7, 0
	v_mov_b32_dpp v56, v60 row_ror:8 row_mask:0xf bank_mask:0xf
	v_mov_b32_dpp v57, v61 row_ror:8 row_mask:0xf bank_mask:0xf
	v_mov_b32_dpp v58, v62 row_ror:8 row_mask:0xf bank_mask:0xf
	v_mov_b32_dpp v59, v63 row_ror:8 row_mask:0xf bank_mask:0xf
	v_mov_b32_dpp v60, v48 row_ror:8 row_mask:0xf bank_mask:0xc
	v_mov_b32_dpp v61, v49 row_ror:8 row_mask:0xf bank_mask:0xc
	v_mov_b32_dpp v62, v50 row_ror:8 row_mask:0xf bank_mask:0xc
	v_mov_b32_dpp v63, v51 row_ror:8 row_mask:0xf bank_mask:0xc
	v_mov_b32_dpp v48, v56 quad_perm:[0,1,2,3] row_mask:0xf bank_mask:0x3
	v_mov_b32_dpp v49, v57 quad_perm:[0,1,2,3] row_mask:0xf bank_mask:0x3
	v_mov_b32_dpp v50, v58 quad_perm:[0,1,2,3] row_mask:0xf bank_mask:0x3
	v_mov_b32_dpp v51, v59 quad_perm:[0,1,2,3] row_mask:0xf bank_mask:0x3
	global_store_dwordx4 v152, v[60:63], s[100:101]
	s_add_u32 s100, s100, 0x10000
	s_addc_u32 s101, s101, 0
	global_store_dwordx4 v152, v[48:51], s[100:101]
	v_cvt_pk_bf16_f32 v52, v52, v53
	v_cvt_pk_bf16_f32 v53, v54, v55
	v_cvt_pk_bf16_f32 v54, v44, v45
	v_cvt_pk_bf16_f32 v55, v46, v47
	v_cvt_pk_bf16_f32 v32, v32, v33
	v_cvt_pk_bf16_f32 v33, v34, v35
	v_cvt_pk_bf16_f32 v34, v24, v25
	v_cvt_pk_bf16_f32 v35, v26, v27
	s_add_u32 s100, s6, 0x120000
	s_addc_u32 s101, s7, 0
	v_mov_b32_dpp v44, v52 row_ror:8 row_mask:0xf bank_mask:0xf
	v_mov_b32_dpp v45, v53 row_ror:8 row_mask:0xf bank_mask:0xf
	v_mov_b32_dpp v46, v54 row_ror:8 row_mask:0xf bank_mask:0xf
	v_mov_b32_dpp v47, v55 row_ror:8 row_mask:0xf bank_mask:0xf
	v_mov_b32_dpp v52, v32 row_ror:8 row_mask:0xf bank_mask:0xc
	v_mov_b32_dpp v53, v33 row_ror:8 row_mask:0xf bank_mask:0xc
	v_mov_b32_dpp v54, v34 row_ror:8 row_mask:0xf bank_mask:0xc
	v_mov_b32_dpp v55, v35 row_ror:8 row_mask:0xf bank_mask:0xc
	v_mov_b32_dpp v32, v44 quad_perm:[0,1,2,3] row_mask:0xf bank_mask:0x3
	v_mov_b32_dpp v33, v45 quad_perm:[0,1,2,3] row_mask:0xf bank_mask:0x3
	v_mov_b32_dpp v34, v46 quad_perm:[0,1,2,3] row_mask:0xf bank_mask:0x3
	v_mov_b32_dpp v35, v47 quad_perm:[0,1,2,3] row_mask:0xf bank_mask:0x3
	global_store_dwordx4 v152, v[52:55], s[100:101]
	s_add_u32 s100, s100, 0x10000
	s_addc_u32 s101, s101, 0
	global_store_dwordx4 v152, v[32:35], s[100:101]
	v_cvt_pk_bf16_f32 v36, v36, v37
	v_cvt_pk_bf16_f32 v37, v38, v39
	v_cvt_pk_bf16_f32 v38, v28, v29
	v_cvt_pk_bf16_f32 v39, v30, v31
	v_cvt_pk_bf16_f32 v16, v16, v17
	v_cvt_pk_bf16_f32 v17, v18, v19
	v_cvt_pk_bf16_f32 v18, v8, v9
	v_cvt_pk_bf16_f32 v19, v10, v11
	s_add_u32 s100, s6, 0x140000
	s_addc_u32 s101, s7, 0
	v_mov_b32_dpp v28, v36 row_ror:8 row_mask:0xf bank_mask:0xf
	v_mov_b32_dpp v29, v37 row_ror:8 row_mask:0xf bank_mask:0xf
	v_mov_b32_dpp v30, v38 row_ror:8 row_mask:0xf bank_mask:0xf
	v_mov_b32_dpp v31, v39 row_ror:8 row_mask:0xf bank_mask:0xf
	v_mov_b32_dpp v36, v16 row_ror:8 row_mask:0xf bank_mask:0xc
	v_mov_b32_dpp v37, v17 row_ror:8 row_mask:0xf bank_mask:0xc
	v_mov_b32_dpp v38, v18 row_ror:8 row_mask:0xf bank_mask:0xc
	v_mov_b32_dpp v39, v19 row_ror:8 row_mask:0xf bank_mask:0xc
	v_mov_b32_dpp v16, v28 quad_perm:[0,1,2,3] row_mask:0xf bank_mask:0x3
	v_mov_b32_dpp v17, v29 quad_perm:[0,1,2,3] row_mask:0xf bank_mask:0x3
	v_mov_b32_dpp v18, v30 quad_perm:[0,1,2,3] row_mask:0xf bank_mask:0x3
	v_mov_b32_dpp v19, v31 quad_perm:[0,1,2,3] row_mask:0xf bank_mask:0x3
	global_store_dwordx4 v152, v[36:39], s[100:101]
	s_add_u32 s100, s100, 0x10000
	s_addc_u32 s101, s101, 0
	global_store_dwordx4 v152, v[16:19], s[100:101]
	v_cvt_pk_bf16_f32 v20, v20, v21
	v_cvt_pk_bf16_f32 v21, v22, v23
	v_cvt_pk_bf16_f32 v22, v12, v13
	v_cvt_pk_bf16_f32 v23, v14, v15
	v_cvt_pk_bf16_f32 v4, v4, v5
	v_cvt_pk_bf16_f32 v5, v6, v7
	v_cvt_pk_bf16_f32 v6, v0, v1
	v_cvt_pk_bf16_f32 v7, v2, v3
	s_add_u32 s100, s6, 0x160000
	s_addc_u32 s101, s7, 0
	v_mov_b32_dpp v12, v20 row_ror:8 row_mask:0xf bank_mask:0xf
	v_mov_b32_dpp v13, v21 row_ror:8 row_mask:0xf bank_mask:0xf
	v_mov_b32_dpp v14, v22 row_ror:8 row_mask:0xf bank_mask:0xf
	v_mov_b32_dpp v15, v23 row_ror:8 row_mask:0xf bank_mask:0xf
	v_mov_b32_dpp v20, v4 row_ror:8 row_mask:0xf bank_mask:0xc
	v_mov_b32_dpp v21, v5 row_ror:8 row_mask:0xf bank_mask:0xc
	v_mov_b32_dpp v22, v6 row_ror:8 row_mask:0xf bank_mask:0xc
	v_mov_b32_dpp v23, v7 row_ror:8 row_mask:0xf bank_mask:0xc
	v_mov_b32_dpp v4, v12 quad_perm:[0,1,2,3] row_mask:0xf bank_mask:0x3
	v_mov_b32_dpp v5, v13 quad_perm:[0,1,2,3] row_mask:0xf bank_mask:0x3
	v_mov_b32_dpp v6, v14 quad_perm:[0,1,2,3] row_mask:0xf bank_mask:0x3
	v_mov_b32_dpp v7, v15 quad_perm:[0,1,2,3] row_mask:0xf bank_mask:0x3
	global_store_dwordx4 v152, v[20:23], s[100:101]
	s_add_u32 s100, s100, 0x10000
	s_addc_u32 s101, s101, 0
	global_store_dwordx4 v152, v[4:7], s[100:101]
	s_andn2_b64 vcc, exec, s[0:1]
	s_mov_b64 s[0:1], -1
	s_cbranch_vccnz .LBB0_592
	s_andn2_b64 vcc, exec, s[4:5]
	s_cbranch_vccnz .LBB0_591
	s_barrier
	s_branch .LBB0_591
